# combo: batched gate loads + GLA table loads batched in both passes + cumsum LDS reads batched + dead log-guard removal
# speedup vs baseline: 1.0069x; 1.0057x over previous
; template <int TYPE>
; __device__ __forceinline__ LgRaw lg_issue(const bf16_t* u, int h, int dir, size_t tok0, int tid) {
;     LgRaw r;
;     if constexpr (TYPE == 1) {
;         const int i0 = tid >> 4, d8 = tid & 15, col = (dir ? C_HFB : C_HFF) + h * 128 + d8 * 8;
;         r.a0 = *(const bf16x8*)(u + (tok0 + i0) * DINP + col); r.a1 = *(const bf16x8*)(u + (tok0 + 32 + i0) * DINP + col); r.k = r.a0;
;     } else {
;         const int i = tid >> 3, d8 = tid & 7; const bf16_t* ur = u + (tok0 + i) * DINP;
;         r.a0 = *(const bf16x8*)(ur + (dir ? C_GAB : C_GAF)); r.a1 = *(const bf16x8*)(ur + (dir ? C_GAB : C_GAF) + 8); r.k = *(const bf16x8*)(ur + C_GK + h * 64 + d8 * 8);
;     }
;     return r;
; }
; template <int TYPE>
; __device__ __forceinline__ void lg_compute(const KArgs& a, unsigned char* wsb, int l, int h, int dir, const LgRaw& raw, LAS unsigned char* lds, int tid) {
;     using C = Cfg<TYPE>;
;     LAS float* G = (LAS float*)(lds + SC_G); LAS bf16_t* Kb = (LAS bf16_t*)(lds + SC_K);
;     if constexpr (TYPE == 1) {
;         const float* lbp = (const float*)(wsb + WS_LB) + (dir * DEPTH + l) * 512 + h * 128;
;         const int d8 = tid & 15;
;         const f32x4 lb0 = *(const f32x4*)(lbp + d8 * 8), lb1 = *(const f32x4*)(lbp + d8 * 8 + 4);
;         const float lb[8] = {lb0[0], lb0[1], lb0[2], lb0[3], lb1[0], lb1[1], lb1[2], lb1[3]};
; #pragma unroll
;         for (int e2 = 0; e2 < 2; ++e2) { const int i = (tid >> 4) + 32 * e2;
;             float z[8], lg[8], kk[8]; unpack8(e2 ? raw.a1 : raw.a0, z);
; #pragma unroll
;             for (int e = 0; e < 8; ++e) { const float sg = sigmoid_(fmaxf(z[e], -80.f)); lg[e] = __logf(lb[e] + (1.f - lb[e]) * sg); kk[e] = (1.f - lb[e]) * (1.f - sg); }
;             *(LAS f32x4*)(G + i * C::LDG + d8 * 8) = (f32x4){lg[0], lg[1], lg[2], lg[3]}; *(LAS f32x4*)(G + i * C::LDG + d8 * 8 + 4) = (f32x4){lg[4], lg[5], lg[6], lg[7]};
;             *(LAS bf16x8*)(Kb + i * C::LDK_ + d8 * 8) = pack8(kk); }
; template <int TYPE>
; __device__ __forceinline__ void pass1_item(const KArgs& a, int l, int item, LAS unsigned char* lds) {
;     unsigned char* const wsb = opq(a.ws);
;     const int tid = opaque_tid();
;     using C = Cfg<TYPE>; constexpr int DK = C::DK;
;     const int c = item & (NCH - 1), dir = (item >> 8) & 1, h = (item >> 9) & 3, b = item >> 11;
;     const size_t tok0 = (size_t)b * T + (size_t)c * 64;
.LBB0_265:
	s_ashr_i32 s4, s15, 11
	s_ashr_i32 s5, s4, 31
	s_lshl_b64 s[4:5], s[4:5], 14
	s_and_b32 s6, s14, 0x3fc0
	s_mov_b64 s[12:13], s[68:69]
	s_bfe_i32 s24, s15, 0x10008
	s_bfe_u32 s16, s15, 0x10008
	s_or_b32 s4, s4, s6
	s_add_u32 s6, s12, 0xe300000
	s_addc_u32 s7, s13, 0
	s_lshr_b32 s17, s15, 2
	s_and_b32 s31, s17, 0x180
	v_mov_b32_e32 v12, v195
	s_cmp_eq_u32 s16, 0
	s_cselect_b64 vcc, -1, 0
	v_ashrrev_i32_e32 v8, 4, v12
	s_and_b64 s[18:19], vcc, exec
	s_movk_i32 s17, 0x820
	v_ashrrev_i32_e32 v9, 31, v8
	s_cselect_b32 s34, s17, 0xa20
	v_lshl_add_u64 v[0:1], s[4:5], 0, v[8:9]
	v_mov_b64_e32 v[2:3], s[6:7]
	s_cselect_b32 s30, 1, 14
	s_cselect_b32 s29, 2, 13
	s_cselect_b32 s28, 3, 12
	s_cselect_b32 s27, 4, 11
	s_cselect_b32 s26, 5, 10
	s_cselect_b32 s25, 6, 9
	s_cselect_b32 s23, 9, 6
	s_cselect_b32 s22, 10, 5
	s_cselect_b32 s21, 11, 4
	s_cselect_b32 s20, 12, 3
	s_cselect_b32 s19, 13, 2
	s_cselect_b32 s18, 14, 1
	s_cselect_b32 s17, 15, 0
	s_or_b32 s36, s34, s31
	v_mad_u64_u32 v[2:3], s[34:35], v0, s2, v[2:3]
	s_mulk_i32 s5, 0x2a00
	s_mul_hi_u32 s34, s4, 0x2a00
	s_add_i32 s34, s34, s5
	s_mulk_i32 s4, 0x2a00
	s_add_u32 s4, s6, s4
	s_addc_u32 s5, s7, s34
	s_lshl_b32 s6, s31, 1
	s_add_u32 s4, s4, s6
	s_addc_u32 s5, s5, 0
	v_lshlrev_b32_e32 v13, 3, v12
	s_add_u32 s4, s4, 0x1840
	v_and_b32_e32 v35, 0x78, v13
	s_addc_u32 s5, s5, 0
	v_mad_i32_i24 v3, v1, s2, v3
	v_add_lshl_u32 v112, s36, v35, 1
	v_mov_b64_e32 v[0:1], s[4:5]
	v_lshl_add_u64 v[10:11], v[2:3], 0, v[112:113]
	v_mad_i64_i32 v[2:3], s[4:5], v8, s2, v[0:1]
	v_lshlrev_b32_e32 v112, 1, v35
	v_lshl_add_u64 v[26:27], v[2:3], 0, v[112:113]
	v_add_u32_e32 v2, 32, v8
	v_mad_i64_i32 v[0:1], s[4:5], v2, s2, v[0:1]
	s_lshl_b32 s4, s16, 10
	s_or_b32 s72, s4, s56
	s_lshl_b64 s[4:5], s[72:73], 2
	s_add_u32 s4, s12, s4
	s_addc_u32 s5, s13, s5
	s_lshl_b32 s6, s31, 2
	s_add_u32 s4, s4, s6
	s_addc_u32 s5, s5, 0
	v_lshlrev_b32_e32 v14, 2, v35
	v_mov_b32_e32 v15, v113
	v_lshl_add_u64 v[30:31], v[0:1], 0, v[112:113]
	v_lshl_add_u64 v[0:1], s[4:5], 0, v[14:15]
	s_mov_b64 s[4:5], 0x3e200000
	v_lshl_add_u64 v[2:3], v[0:1], 0, s[4:5]
	s_mov_b32 s4, 0x3e200000
	v_add_co_u32_e64 v0, s[4:5], s4, v0
	s_waitcnt lgkmcnt(0)
	s_nop 0
	v_addc_co_u32_e64 v1, s[4:5], 0, v1, s[4:5]
	s_barrier
	global_load_dwordx4 v[4:7], v[0:1], off
	s_nop 0
	global_load_dwordx4 v[0:3], v[2:3], off offset:16
	v_add_u32_e32 v22, 0, v14
	global_load_dwordx4 v[14:17], v[10:11], off
	v_sub_u32_e32 v34, v22, v112
	s_movk_i32 s0, 0xff81
	s_waitcnt vmcnt(0) lgkmcnt(0)
	v_pk_add_f32 v[36:37], v[4:5], 1.0 op_sel_hi:[1,0] neg_lo:[1,0] neg_hi:[1,0]
	v_pk_add_f32 v[40:41], v[6:7], 1.0 op_sel_hi:[1,0] neg_lo:[1,0] neg_hi:[1,0]
	v_pk_add_f32 v[44:45], v[0:1], 1.0 op_sel_hi:[1,0] neg_lo:[1,0] neg_hi:[1,0]
	v_lshlrev_b32_e32 v9, 16, v14
	v_max_f32_e32 v9, v9, v9
	v_max_f32_e32 v9, 0xc2a00000, v9
	v_mul_f32_e32 v9, 0xbfb8aa3b, v9
	v_exp_f32_e32 v9, v9
	v_and_b32_e32 v14, 0xffff0000, v14
	v_lshlrev_b32_e32 v23, 16, v16
	v_and_b32_e32 v24, 0xffff0000, v16
	v_add_f32_e32 v9, 1.0, v9
	v_rcp_f32_e32 v16, v9
	v_max_f32_e32 v9, v14, v14
	v_max_f32_e32 v9, 0xc2a00000, v9
	v_mul_f32_e32 v9, 0xbfb8aa3b, v9
	v_exp_f32_e32 v9, v9
	v_lshlrev_b32_e32 v28, 16, v17
	v_and_b32_e32 v29, 0xffff0000, v17
	v_lshlrev_b32_e32 v20, 16, v15
	v_add_f32_e32 v9, 1.0, v9
	v_rcp_f32_e32 v17, v9
	v_fma_f32 v9, v36, v16, v4
	v_and_b32_e32 v21, 0xffff0000, v15
	v_pk_add_f32 v[18:19], v[16:17], 1.0 op_sel_hi:[1,0] neg_lo:[1,0] neg_hi:[1,0]
	v_log_f32_e32 v9, v9
	v_pk_mul_f32 v[38:39], v[36:37], v[18:19]
	v_pk_add_f32 v[48:49], v[2:3], 1.0 op_sel_hi:[1,0] neg_lo:[1,0] neg_hi:[1,0]
	v_mul_f32_e32 v14, 0x3f317217, v9
	v_fma_f32 v14, v9, s92, -v14
	v_fmac_f32_e32 v14, 0x3377d1cf, v9
	v_fmac_f32_e32 v14, 0x3f317217, v9
	s_nop 1
	v_mov_b32_e32 v9, v14
	v_fma_f32 v9, v37, v17, v5
	s_nop 1
	v_log_f32_e32 v9, v9
	s_nop 0
	v_mul_f32_e32 v15, 0x3f317217, v9
	v_fma_f32 v15, v9, s92, -v15
	v_fmac_f32_e32 v15, 0x3377d1cf, v9
	v_fmac_f32_e32 v15, 0x3f317217, v9
	s_nop 1
	v_mov_b32_e32 v9, v15
	v_max_f32_e32 v9, v20, v20
	v_max_f32_e32 v9, 0xc2a00000, v9
	v_mul_f32_e32 v9, 0xbfb8aa3b, v9
	v_exp_f32_e32 v9, v9
	s_nop 0
	v_add_f32_e32 v9, 1.0, v9
	v_rcp_f32_e32 v18, v9
	v_max_f32_e32 v9, v21, v21
	v_max_f32_e32 v9, 0xc2a00000, v9
	v_mul_f32_e32 v9, 0xbfb8aa3b, v9
	v_exp_f32_e32 v9, v9
	s_nop 0
	v_add_f32_e32 v9, 1.0, v9
	v_rcp_f32_e32 v19, v9
	v_fma_f32 v9, v40, v18, v6
	v_pk_add_f32 v[20:21], v[18:19], 1.0 op_sel_hi:[1,0] neg_lo:[1,0] neg_hi:[1,0]
	s_nop 0
	v_log_f32_e32 v9, v9
	v_pk_mul_f32 v[42:43], v[40:41], v[20:21]
	v_mul_f32_e32 v16, 0x3f317217, v9
	v_fma_f32 v16, v9, s92, -v16
	v_fmac_f32_e32 v16, 0x3377d1cf, v9
	v_fmac_f32_e32 v16, 0x3f317217, v9
	s_nop 1
	v_mov_b32_e32 v9, v16
	v_fma_f32 v9, v41, v19, v7
	s_nop 1
	v_log_f32_e32 v9, v9
	s_nop 0
	v_mul_f32_e32 v17, 0x3f317217, v9
	v_fma_f32 v17, v9, s92, -v17
	v_fmac_f32_e32 v17, 0x3377d1cf, v9
	v_fmac_f32_e32 v17, 0x3f317217, v9
	s_nop 1
	v_mov_b32_e32 v9, v17
	v_max_f32_e32 v9, v23, v23
	v_max_f32_e32 v9, 0xc2a00000, v9
	v_mul_f32_e32 v9, 0xbfb8aa3b, v9
	v_exp_f32_e32 v9, v9
	s_nop 0
	v_add_f32_e32 v9, 1.0, v9
	v_rcp_f32_e32 v20, v9
	v_max_f32_e32 v9, v24, v24
	v_max_f32_e32 v9, 0xc2a00000, v9
	v_mul_f32_e32 v9, 0xbfb8aa3b, v9
	v_exp_f32_e32 v9, v9
	s_nop 0
	v_add_f32_e32 v9, 1.0, v9
	v_rcp_f32_e32 v21, v9
	v_fma_f32 v9, v44, v20, v0
	v_pk_add_f32 v[24:25], v[20:21], 1.0 op_sel_hi:[1,0] neg_lo:[1,0] neg_hi:[1,0]
	s_nop 0
	v_log_f32_e32 v9, v9
	v_pk_mul_f32 v[46:47], v[44:45], v[24:25]
	v_mul_f32_e32 v18, 0x3f317217, v9
	v_fma_f32 v18, v9, s92, -v18
	v_fmac_f32_e32 v18, 0x3377d1cf, v9
	v_fmac_f32_e32 v18, 0x3f317217, v9
	s_nop 1
	v_mov_b32_e32 v9, v18
; #define LAS __attribute__((address_space(3)))
; __device__ __forceinline__ float sigmoid_(float z) { return __builtin_amdgcn_rcpf(1.f + __expf(-z)); }
; template <int TYPE>
; __device__ __forceinline__ void lg_compute(const KArgs& a, unsigned char* wsb, int l, int h, int dir, const LgRaw& raw, LAS unsigned char* lds, int tid) {
;     ...
;         for (int e2 = 0; e2 < 2; ++e2) { const int i = (tid >> 4) + 32 * e2;
;             float z[8], lg[8], kk[8]; unpack8(e2 ? raw.a1 : raw.a0, z);
; #pragma unroll
;             for (int e = 0; e < 8; ++e) { const float sg = sigmoid_(fmaxf(z[e], -80.f)); lg[e] = __logf(lb[e] + (1.f - lb[e]) * sg); kk[e] = (1.f - lb[e]) * (1.f - sg); }
;             *(LAS f32x4*)(G + i * C::LDG + d8 * 8) = (f32x4){lg[0], lg[1], lg[2], lg[3]}; *(LAS f32x4*)(G + i * C::LDG + d8 * 8 + 4) = (f32x4){lg[4], lg[5], lg[6], lg[7]};
;             *(LAS bf16x8*)(Kb + i * C::LDK_ + d8 * 8) = pack8(kk); }
	v_fma_f32 v9, v45, v21, v1
	s_nop 1
	v_log_f32_e32 v9, v9
	s_nop 0
	v_mul_f32_e32 v19, 0x3f317217, v9
	v_fma_f32 v19, v9, s92, -v19
	v_fmac_f32_e32 v19, 0x3377d1cf, v9
	v_fmac_f32_e32 v19, 0x3f317217, v9
	s_nop 1
	v_mov_b32_e32 v9, v19
	v_max_f32_e32 v9, v28, v28
	v_max_f32_e32 v9, 0xc2a00000, v9
	v_mul_f32_e32 v9, 0xbfb8aa3b, v9
	v_exp_f32_e32 v9, v9
	s_nop 0
	v_add_f32_e32 v9, 1.0, v9
	v_rcp_f32_e32 v24, v9
	v_max_f32_e32 v9, v29, v29
	v_max_f32_e32 v9, 0xc2a00000, v9
	v_mul_f32_e32 v9, 0xbfb8aa3b, v9
	v_exp_f32_e32 v9, v9
	s_nop 0
	v_add_f32_e32 v9, 1.0, v9
	v_rcp_f32_e32 v25, v9
	v_fma_f32 v9, v48, v24, v2
	v_pk_add_f32 v[28:29], v[24:25], 1.0 op_sel_hi:[1,0] neg_lo:[1,0] neg_hi:[1,0]
	s_nop 0
	v_log_f32_e32 v9, v9
	v_pk_mul_f32 v[50:51], v[48:49], v[28:29]
	v_mul_f32_e32 v20, 0x3f317217, v9
	v_fma_f32 v20, v9, s92, -v20
	v_fmac_f32_e32 v20, 0x3377d1cf, v9
	v_fmac_f32_e32 v20, 0x3f317217, v9
	s_nop 1
	v_mov_b32_e32 v9, v20
	v_fma_f32 v9, v49, v25, v3
	s_nop 1
	v_log_f32_e32 v9, v9
	s_nop 0
	v_mul_f32_e32 v21, 0x3f317217, v9
	v_fma_f32 v21, v9, s92, -v21
	v_fmac_f32_e32 v21, 0x3377d1cf, v9
	v_fmac_f32_e32 v21, 0x3f317217, v9
	s_nop 1
	v_mov_b32_e32 v9, v21
	v_mad_u64_u32 v[52:53], s[4:5], v8, s91, v[22:23]
	s_mov_b32 s4, 0x54000
	s_nop 0
	v_add_co_u32_e64 v10, s[4:5], s4, v10
	s_nop 0
	v_addc_co_u32_e64 v11, s[4:5], 0, v11, s[4:5]
	global_load_dwordx4 v[22:25], v[10:11], off
	s_nop 0
	global_load_dwordx4 v[26:29], v[26:27], off
	s_nop 0
	global_load_dwordx4 v[30:33], v[30:31], off
	ds_write_b128 v52, v[14:17]
	ds_write_b128 v52, v[18:21] offset:16
	v_cvt_pk_bf16_f32 v14, v38, v39
	v_cvt_pk_bf16_f32 v15, v42, v43
	v_cvt_pk_bf16_f32 v16, v46, v47
	v_cvt_pk_bf16_f32 v17, v50, v51
	v_mad_u64_u32 v[10:11], s[4:5], v8, s93, v[34:35]
	ds_write_b128 v10, v[14:17] offset:33792
	s_waitcnt vmcnt(0) lgkmcnt(0)
	v_lshlrev_b32_e32 v9, 16, v22
	v_max_f32_e32 v9, v9, v9
	v_max_f32_e32 v9, 0xc2a00000, v9
	v_mul_f32_e32 v9, 0xbfb8aa3b, v9
	v_exp_f32_e32 v9, v9
	v_and_b32_e32 v11, 0xffff0000, v22
	v_lshlrev_b32_e32 v16, 16, v23
	v_and_b32_e32 v17, 0xffff0000, v23
	v_add_f32_e32 v9, 1.0, v9
	v_rcp_f32_e32 v14, v9
	v_lshlrev_b32_e32 v18, 16, v24
	v_and_b32_e32 v19, 0xffff0000, v24
	v_lshlrev_b32_e32 v20, 16, v25
	v_fma_f32 v4, v36, v14, v4
	v_and_b32_e32 v21, 0xffff0000, v25
	s_nop 0
	v_log_f32_e32 v4, v4
	s_nop 0
	v_mul_f32_e32 v9, 0x3f317217, v4
	v_fma_f32 v9, v4, s92, -v9
	v_fmac_f32_e32 v9, 0x3377d1cf, v4
	v_fmac_f32_e32 v9, 0x3f317217, v4
	s_nop 1
	v_mov_b32_e32 v4, v9
	v_max_f32_e32 v9, v11, v11
	v_max_f32_e32 v9, 0xc2a00000, v9
	v_mul_f32_e32 v9, 0xbfb8aa3b, v9
	v_exp_f32_e32 v9, v9
	s_nop 0
	v_add_f32_e32 v9, 1.0, v9
	v_rcp_f32_e32 v15, v9
	s_nop 0
	v_fma_f32 v5, v37, v15, v5
	v_pk_add_f32 v[14:15], v[14:15], 1.0 op_sel_hi:[1,0] neg_lo:[1,0] neg_hi:[1,0]
	s_nop 0
	v_log_f32_e32 v5, v5
	v_pk_mul_f32 v[14:15], v[36:37], v[14:15]
	v_mul_f32_e32 v9, 0x3f317217, v5
	v_fma_f32 v9, v5, s92, -v9
	v_fmac_f32_e32 v9, 0x3377d1cf, v5
	v_fmac_f32_e32 v9, 0x3f317217, v5
	s_nop 1
	v_mov_b32_e32 v5, v9
	v_max_f32_e32 v9, v16, v16
	v_max_f32_e32 v9, 0xc2a00000, v9
	v_mul_f32_e32 v9, 0xbfb8aa3b, v9
	v_exp_f32_e32 v9, v9
	s_nop 0
	v_add_f32_e32 v9, 1.0, v9
	v_rcp_f32_e32 v16, v9
	s_nop 0
	v_fma_f32 v6, v40, v16, v6
	s_nop 1
	v_log_f32_e32 v6, v6
	s_nop 0
	v_mul_f32_e32 v9, 0x3f317217, v6
	v_fma_f32 v9, v6, s92, -v9
	v_fmac_f32_e32 v9, 0x3377d1cf, v6
	v_fmac_f32_e32 v9, 0x3f317217, v6
	s_nop 1
	v_mov_b32_e32 v6, v9
	v_max_f32_e32 v9, v17, v17
	v_max_f32_e32 v9, 0xc2a00000, v9
	v_mul_f32_e32 v9, 0xbfb8aa3b, v9
	v_exp_f32_e32 v9, v9
	s_nop 0
	v_add_f32_e32 v9, 1.0, v9
	v_rcp_f32_e32 v17, v9
	s_nop 0
	v_fmac_f32_e32 v7, v41, v17
	v_pk_add_f32 v[16:17], v[16:17], 1.0 op_sel_hi:[1,0] neg_lo:[1,0] neg_hi:[1,0]
	s_nop 0
	v_log_f32_e32 v7, v7
	v_pk_mul_f32 v[16:17], v[40:41], v[16:17]
	v_mul_f32_e32 v9, 0x3f317217, v7
	v_fma_f32 v9, v7, s92, -v9
	v_fmac_f32_e32 v9, 0x3377d1cf, v7
	v_fmac_f32_e32 v9, 0x3f317217, v7
	s_nop 1
	v_mov_b32_e32 v7, v9
	v_max_f32_e32 v9, v18, v18
	v_max_f32_e32 v9, 0xc2a00000, v9
	v_mul_f32_e32 v9, 0xbfb8aa3b, v9
	v_exp_f32_e32 v9, v9
	s_nop 0
	v_add_f32_e32 v9, 1.0, v9
	v_rcp_f32_e32 v18, v9
	s_nop 0
	v_fma_f32 v0, v44, v18, v0
	s_nop 1
	v_log_f32_e32 v0, v0
	s_nop 0
	v_mul_f32_e32 v9, 0x3f317217, v0
	v_fma_f32 v9, v0, s92, -v9
	v_fmac_f32_e32 v9, 0x3377d1cf, v0
	v_fmac_f32_e32 v9, 0x3f317217, v0
	s_nop 1
	v_mov_b32_e32 v0, v9
	v_max_f32_e32 v9, v19, v19
	v_max_f32_e32 v9, 0xc2a00000, v9
	v_mul_f32_e32 v9, 0xbfb8aa3b, v9
	v_exp_f32_e32 v9, v9
	s_nop 0
	v_add_f32_e32 v9, 1.0, v9
	v_rcp_f32_e32 v19, v9
	s_nop 0
	v_fma_f32 v1, v45, v19, v1
	v_pk_add_f32 v[18:19], v[18:19], 1.0 op_sel_hi:[1,0] neg_lo:[1,0] neg_hi:[1,0]
	s_nop 0
	v_log_f32_e32 v1, v1
	v_pk_mul_f32 v[18:19], v[44:45], v[18:19]
	v_mul_f32_e32 v9, 0x3f317217, v1
	v_fma_f32 v9, v1, s92, -v9
	v_fmac_f32_e32 v9, 0x3377d1cf, v1
	v_fmac_f32_e32 v9, 0x3f317217, v1
	s_nop 1
	v_mov_b32_e32 v1, v9
	v_max_f32_e32 v9, v20, v20
	v_max_f32_e32 v9, 0xc2a00000, v9
; #define LAS __attribute__((address_space(3)))
; __device__ __forceinline__ float sigmoid_(float z) { return __builtin_amdgcn_rcpf(1.f + __expf(-z)); }
; template <int TYPE>
; __device__ __forceinline__ void lg_compute(const KArgs& a, unsigned char* wsb, int l, int h, int dir, const LgRaw& raw, LAS unsigned char* lds, int tid) {
;     ...
;         for (int e2 = 0; e2 < 2; ++e2) { const int i = (tid >> 4) + 32 * e2;
;             float z[8], lg[8], kk[8]; unpack8(e2 ? raw.a1 : raw.a0, z);
; #pragma unroll
;             for (int e = 0; e < 8; ++e) { const float sg = sigmoid_(fmaxf(z[e], -80.f)); lg[e] = __logf(lb[e] + (1.f - lb[e]) * sg); kk[e] = (1.f - lb[e]) * (1.f - sg); }
;             *(LAS f32x4*)(G + i * C::LDG + d8 * 8) = (f32x4){lg[0], lg[1], lg[2], lg[3]}; *(LAS f32x4*)(G + i * C::LDG + d8 * 8 + 4) = (f32x4){lg[4], lg[5], lg[6], lg[7]};
;             *(LAS bf16x8*)(Kb + i * C::LDK_ + d8 * 8) = pack8(kk); }
; template <int TYPE>
; __device__ __forceinline__ void cumsum_g(int dir, LAS unsigned char* lds, int tid) {
;     using C = Cfg<TYPE>; constexpr int NSEG = 512 / C::DK, SEGL = 64 / NSEG;
;     LAS float* G = (LAS float*)(lds + SC_G); LAS float* SG = (LAS float*)(lds + SC_SEG);
;     const int d = tid % C::DK, seg = tid / C::DK;
;     __syncthreads();
;     float run = 0.f;
; #pragma unroll
;     for (int ii = 0; ii < SEGL; ++ii) { const int i = seg * SEGL + (dir ? SEGL - 1 - ii : ii); run += G[i * C::LDG + d]; G[i * C::LDG + d] = run; }
;     SG[seg * 128 + d] = run;
;     __syncthreads();
;     float off = 0.f;
; #pragma unroll
;     for (int s = 0; s < NSEG; ++s) { const bool before = dir ? (s > seg) : (s < seg); if (before) off += SG[s * 128 + d]; }
; #pragma unroll
;     for (int ii = 0; ii < SEGL; ++ii) { const int i = seg * SEGL + ii; G[i * C::LDG + d] += off; }
;     __syncthreads();
; }
; __device__ __forceinline__ void vT_write(const VRaw& r, LAS unsigned char* lds, int tid) {
;     LAS bf16_t* VT = (LAS bf16_t*)(lds + SC_VT);
;     const int v8 = tid & 15;
; #pragma unroll
;     for (int e2 = 0; e2 < 2; ++e2) { const int i = (tid >> 4) + 32 * e2; const bf16x8 x = e2 ? r.x1 : r.x0; const int pc = ((((i >> 3) ^ (v8 & 7)) << 3) | (i & 7));
; #pragma unroll
;         for (int e = 0; e < 8; ++e) VT[(v8 * 8 + e) * LDT + pc] = (bf16_t)x[e]; }
; }
	v_mul_f32_e32 v9, 0xbfb8aa3b, v9
	v_exp_f32_e32 v9, v9
	s_nop 0
	v_add_f32_e32 v9, 1.0, v9
	v_rcp_f32_e32 v20, v9
	s_nop 0
	v_fma_f32 v2, v48, v20, v2
	s_nop 1
	v_log_f32_e32 v2, v2
	s_nop 0
	v_mul_f32_e32 v9, 0x3f317217, v2
	v_fma_f32 v9, v2, s92, -v9
	v_fmac_f32_e32 v9, 0x3377d1cf, v2
	v_fmac_f32_e32 v9, 0x3f317217, v2
	s_nop 1
	v_mov_b32_e32 v2, v9
	v_max_f32_e32 v9, v21, v21
	v_max_f32_e32 v9, 0xc2a00000, v9
	v_mul_f32_e32 v9, 0xbfb8aa3b, v9
	v_exp_f32_e32 v9, v9
	s_nop 0
	v_add_f32_e32 v9, 1.0, v9
	v_rcp_f32_e32 v21, v9
	s_nop 0
	v_fmac_f32_e32 v3, v49, v21
	v_pk_add_f32 v[20:21], v[20:21], 1.0 op_sel_hi:[1,0] neg_lo:[1,0] neg_hi:[1,0]
	s_nop 0
	v_log_f32_e32 v3, v3
	v_pk_mul_f32 v[20:21], v[48:49], v[20:21]
	v_mul_f32_e32 v9, 0x3f317217, v3
	v_fma_f32 v9, v3, s92, -v9
	v_fmac_f32_e32 v9, 0x3377d1cf, v3
	v_fmac_f32_e32 v9, 0x3f317217, v3
	s_nop 1
	v_mov_b32_e32 v3, v9
	ds_write_b128 v52, v[4:7] offset:16896
	ds_write_b128 v52, v[0:3] offset:16912
	v_cvt_pk_bf16_f32 v0, v14, v15
	v_cvt_pk_bf16_f32 v1, v16, v17
	v_cvt_pk_bf16_f32 v2, v18, v19
	v_cvt_pk_bf16_f32 v3, v20, v21
	ds_write_b128 v10, v[0:3] offset:42496
	v_and_b32_e32 v0, 56, v13
	v_lshlrev_b32_e32 v1, 1, v8
	v_and_b32_e32 v1, 14, v1
	v_bitop3_b32 v0, v8, v0, -8 bitop3:0x6c
	v_add_u32_e32 v1, s95, v1
	v_lshlrev_b32_e32 v0, 1, v0
	v_mul_u32_u24_e32 v3, 0x90, v35
	v_and_b32_e32 v2, -8, v8
	v_add3_u32 v0, v1, v0, v3
	ds_write_b16 v0, v26
	ds_write_b16_d16_hi v0, v26 offset:144
	ds_write_b16 v0, v27 offset:288
	ds_write_b16_d16_hi v0, v27 offset:432
	ds_write_b16 v0, v28 offset:576
	ds_write_b16_d16_hi v0, v28 offset:720
	ds_write_b16 v0, v29 offset:864
	ds_write_b16_d16_hi v0, v29 offset:1008
	v_add_u32_e32 v0, 32, v2
	v_bitop3_b32 v0, v0, v13, 56 bitop3:0x78
	v_lshlrev_b32_e32 v0, 1, v0
	v_add3_u32 v0, v1, v0, v3
	ds_write_b16 v0, v30
	ds_write_b16_d16_hi v0, v30 offset:144
	ds_write_b16 v0, v31 offset:288
	ds_write_b16_d16_hi v0, v31 offset:432
	ds_write_b16 v0, v32 offset:576
	ds_write_b16_d16_hi v0, v32 offset:720
	ds_write_b16 v0, v33 offset:864
	ds_write_b16_d16_hi v0, v33 offset:1008
	v_ashrrev_i32_e32 v0, 31, v12
	v_lshrrev_b32_e32 v0, 25, v0
	v_add_u32_e32 v0, v12, v0
	v_ashrrev_i32_e32 v1, 7, v0
	v_and_b32_e32 v0, 0x3fffff80, v0
	v_sub_u32_e32 v0, v12, v0
	v_lshlrev_b32_e32 v4, 4, v1
	v_lshlrev_b32_e32 v5, 2, v0
	v_add_u32_e32 v0, 0, v5
	v_and_or_b32 v2, s24, 15, v4
	v_mad_u64_u32 v[2:3], s[4:5], v2, s91, v[0:1]
	s_waitcnt lgkmcnt(0)
	s_barrier
	ds_read_b32 v96, v2
	v_or_b32_e32 v64, s30, v4
	v_mad_u64_u32 v[64:65], s[4:5], v64, s91, v[0:1]
	ds_read_b32 v97, v64
	v_or_b32_e32 v66, s29, v4
	v_mad_u64_u32 v[66:67], s[4:5], v66, s91, v[0:1]
	ds_read_b32 v98, v66
	v_or_b32_e32 v68, s28, v4
	v_mad_u64_u32 v[68:69], s[4:5], v68, s91, v[0:1]
	ds_read_b32 v99, v68
	v_or_b32_e32 v70, s27, v4
	v_mad_u64_u32 v[70:71], s[4:5], v70, s91, v[0:1]
	ds_read_b32 v100, v70
	v_or_b32_e32 v72, s26, v4
	v_mad_u64_u32 v[72:73], s[4:5], v72, s91, v[0:1]
	ds_read_b32 v101, v72
	v_or_b32_e32 v74, s25, v4
	v_mad_u64_u32 v[74:75], s[4:5], v74, s91, v[0:1]
	ds_read_b32 v102, v74
	s_add_i32 s4, s16, 7
	v_or_b32_e32 v76, s4, v4
	v_mad_u64_u32 v[76:77], s[4:5], v76, s91, v[0:1]
	ds_read_b32 v103, v76
	v_subrev_u32_e32 v78, s16, v4
	v_mad_u64_u32 v[78:79], s[4:5], v78, s91, v[0:1]
	ds_read_b32 v104, v78 offset:4224
	v_or_b32_e32 v80, s23, v4
	v_mad_u64_u32 v[80:81], s[4:5], v80, s91, v[0:1]
	ds_read_b32 v105, v80
	v_or_b32_e32 v82, s22, v4
	v_mad_u64_u32 v[82:83], s[4:5], v82, s91, v[0:1]
	ds_read_b32 v106, v82
	v_or_b32_e32 v84, s21, v4
	v_mad_u64_u32 v[84:85], s[4:5], v84, s91, v[0:1]
	ds_read_b32 v107, v84
	v_or_b32_e32 v86, s20, v4
	v_mad_u64_u32 v[86:87], s[4:5], v86, s91, v[0:1]
	ds_read_b32 v108, v86
	v_or_b32_e32 v88, s19, v4
	v_mad_u64_u32 v[88:89], s[4:5], v88, s91, v[0:1]
	ds_read_b32 v109, v88
	v_or_b32_e32 v90, s18, v4
	v_mad_u64_u32 v[90:91], s[4:5], v90, s91, v[0:1]
	ds_read_b32 v110, v90
	v_or_b32_e32 v92, s17, v4
	v_mad_u64_u32 v[92:93], s[4:5], v92, s91, v[0:1]
	ds_read_b32 v111, v92
	v_cmp_gt_i32_e64 s[4:5], s0, v12
	s_movk_i32 s0, 0x7f
	v_cmp_lt_i32_e64 s[6:7], s0, v12
	v_cndmask_b32_e64 v4, 0, 1, s[4:5]
	s_waitcnt lgkmcnt(0)
	v_add_f32_e32 v6, 0, v96
	ds_write_b32 v2, v6
	v_add_f32_e32 v6, v6, v97
	ds_write_b32 v64, v6
	v_add_f32_e32 v6, v6, v98
	ds_write_b32 v66, v6
	v_add_f32_e32 v6, v6, v99
	ds_write_b32 v68, v6
	v_add_f32_e32 v6, v6, v100
	ds_write_b32 v70, v6
	v_add_f32_e32 v6, v6, v101
	ds_write_b32 v72, v6
	v_add_f32_e32 v6, v6, v102
	ds_write_b32 v74, v6
	v_add_f32_e32 v6, v6, v103
	ds_write_b32 v76, v6
	v_add_f32_e32 v6, v6, v104
	ds_write_b32 v78, v6 offset:4224
	v_add_f32_e32 v6, v6, v105
	ds_write_b32 v80, v6
	v_add_f32_e32 v6, v6, v106
	ds_write_b32 v82, v6
	v_add_f32_e32 v6, v6, v107
	ds_write_b32 v84, v6
	v_add_f32_e32 v6, v6, v108
	ds_write_b32 v86, v6
	v_add_f32_e32 v6, v6, v109
	ds_write_b32 v88, v6
	v_add_f32_e32 v6, v6, v110
	ds_write_b32 v90, v6
	v_add_f32_e32 v3, v6, v111
	ds_write_b32 v92, v3


; template <int TYPE>
; __device__ __forceinline__ void cumsum_g(int dir, LAS unsigned char* lds, int tid) {
;     ...
;     for (int ii = 0; ii < SEGL; ++ii) { const int i = seg * SEGL + (dir ? SEGL - 1 - ii : ii); run += G[i * C::LDG + d]; G[i * C::LDG + d] = run; }
;     SG[seg * 128 + d] = run;
;     __syncthreads();
;     float off = 0.f;
; #pragma unroll
;     for (int s = 0; s < NSEG; ++s) { const bool before = dir ? (s > seg) : (s < seg); if (before) off += SG[s * 128 + d]; }
	v_lshl_add_u32 v2, v12, 2, s74
	ds_write_b32 v2, v3
	v_cndmask_b32_e64 v3, 0, 1, s[6:7]
	v_cndmask_b32_e32 v3, v4, v3, vcc
	v_and_b32_e32 v3, 1, v3
	v_add_u32_e32 v2, s74, v5
	v_cmp_eq_u32_e64 s[4:5], 1, v3
	v_mov_b32_e32 v3, 0
	s_waitcnt lgkmcnt(0)
	s_barrier
	s_and_saveexec_b64 s[6:7], s[4:5]
	s_cbranch_execz .LBB0_267
	ds_read_b32 v3, v2
	s_waitcnt lgkmcnt(0)
	v_add_f32_e32 v3, 0, v3

; template <int TYPE>
; __device__ __forceinline__ LgRaw lg_issue(const bf16_t* u, int h, int dir, size_t tok0, int tid) {
;     LgRaw r;
;     if constexpr (TYPE == 1) {
;         const int i0 = tid >> 4, d8 = tid & 15, col = (dir ? C_HFB : C_HFF) + h * 128 + d8 * 8;
;         r.a0 = *(const bf16x8*)(u + (tok0 + i0) * DINP + col); r.a1 = *(const bf16x8*)(u + (tok0 + 32 + i0) * DINP + col); r.k = r.a0;
;     } else {
;         const int i = tid >> 3, d8 = tid & 7; const bf16_t* ur = u + (tok0 + i) * DINP;
;         r.a0 = *(const bf16x8*)(ur + (dir ? C_GAB : C_GAF)); r.a1 = *(const bf16x8*)(ur + (dir ? C_GAB : C_GAF) + 8); r.k = *(const bf16x8*)(ur + C_GK + h * 64 + d8 * 8);
;     }
;     return r;
; template <int TYPE>
; __device__ __forceinline__ void lg_compute(const KArgs& a, unsigned char* wsb, int l, int h, int dir, const LgRaw& raw, LAS unsigned char* lds, int tid) {
;     ...
;     } else {
;         const int i = tid >> 3, d8 = tid & 7;
;         float ua[16]; unpack8(raw.a0, ua); unpack8(raw.a1, ua + 8);
;         const float* up = (const float*)a.in[3] + (size_t)((l * 2 + dir) * 16) * 256 + h * 64 + d8 * 8;
;         const float* bs = (const float*)a.in[4] + (l * 2 + dir) * 256 + h * 64 + d8 * 8;
;         f32x4 z0 = *(const f32x4*)bs, z1 = *(const f32x4*)(bs + 4);
; #pragma unroll
;         for (int r = 0; r < 16; ++r) { z0 += ua[r] * *(const f32x4*)(up + r * 256); z1 += ua[r] * *(const f32x4*)(up + r * 256 + 4); }
.LBB0_288:
	s_ashr_i32 s4, s16, 11
	s_ashr_i32 s5, s4, 31
	s_lshl_b64 s[4:5], s[4:5], 14
	s_and_b32 s6, s15, 0x3fc0
	s_mov_b64 s[12:13], s[68:69]
	v_mov_b32_e32 v12, v195
	s_bfe_i32 s18, s16, 0x10008
	s_bfe_u32 s17, s16, 0x10008
	s_bfe_u32 s19, s16, 0x20009
	s_or_b32 s4, s4, s6
	s_add_u32 s6, s12, 0xe300000
	v_ashrrev_i32_e32 v8, 3, v12
	s_addc_u32 s7, s13, 0
	v_ashrrev_i32_e32 v9, 31, v8
	v_lshl_add_u64 v[0:1], s[4:5], 0, v[8:9]
	v_mov_b64_e32 v[2:3], s[6:7]
	v_mad_u64_u32 v[2:3], s[20:21], v0, s2, v[2:3]
	s_mulk_i32 s5, 0x2a00
	s_mul_hi_u32 s21, s4, 0x2a00
	s_lshl_b32 s20, s19, 7
	s_add_i32 s21, s21, s5
	s_mulk_i32 s4, 0x2a00
	s_add_u32 s4, s6, s4
	s_addc_u32 s5, s7, s21
	s_lshl_b32 s19, s19, 8
	s_add_u32 s4, s4, s19
	s_addc_u32 s5, s5, 0
	s_or_b32 s21, s17, s14
	s_lshl_b32 s72, s21, 12
	v_readlane_b32 s36, v253, 48
	s_lshl_b64 s[6:7], s[72:73], 2
	v_readlane_b32 s42, v253, 54
	v_readlane_b32 s43, v253, 55
	s_add_u32 s6, s42, s6
	s_addc_u32 s7, s43, s7
	s_add_u32 s6, s6, s19
	s_addc_u32 s7, s7, 0
	s_lshl_b32 s72, s21, 8
	v_readlane_b32 s44, v253, 56
	s_lshl_b64 s[22:23], s[72:73], 2
	v_readlane_b32 s45, v253, 57
	s_add_u32 s21, s44, s22
	s_addc_u32 s23, s45, s23
	s_add_u32 s22, s21, s19
	s_addc_u32 s23, s23, 0
	s_add_i32 s19, s17, 3
	s_cmp_eq_u32 s17, 0
	s_cselect_b64 vcc, -1, 0
	s_and_b64 s[24:25], vcc, exec
	s_movk_i32 s21, 0x820
	v_lshlrev_b32_e32 v9, 3, v12
	v_mad_i32_i24 v3, v1, s2, v3
	s_cselect_b32 s72, 0x800, s21
	s_mov_b32 s21, s73
	v_and_b32_e32 v13, 56, v9
	v_ashrrev_i32_e32 v35, 4, v12
	s_movk_i32 s2, 0x2a00
	v_lshl_add_u64 v[0:1], v[2:3], 0, s[20:21]
	v_lshlrev_b32_e32 v112, 1, v13
	v_mov_b64_e32 v[6:7], s[4:5]
	v_and_b32_e32 v37, 0x78, v9
	v_add_u32_e32 v16, 32, v35
	v_lshl_add_u64 v[10:11], v[2:3], 0, s[72:73]
	v_lshl_add_u64 v[0:1], v[0:1], 0, v[112:113]
	v_mad_i64_i32 v[4:5], s[4:5], v35, s2, v[6:7]
	v_lshlrev_b32_e32 v14, 1, v37
	v_mov_b32_e32 v15, v113
	v_mad_i64_i32 v[6:7], s[4:5], v16, s2, v[6:7]
	s_waitcnt lgkmcnt(0)
	s_barrier
	global_load_dwordx4 v[0:3], v[0:1], off offset:512
	v_lshl_add_u64 v[4:5], v[4:5], 0, v[14:15]
	v_lshl_add_u64 v[6:7], v[6:7], 0, v[14:15]
	global_load_dwordx4 v[14:17], v[10:11], off
	global_load_dwordx4 v[64:67], v[10:11], off offset:16
	v_lshlrev_b32_e32 v68, 2, v13
	v_add_u32_e32 v69, 0x1000, v68
	v_add_u32_e32 v94, 0x2000, v68
	v_add_u32_e32 v95, 0x3000, v68
	s_mov_b64 s[4:5], 0x1000
	s_movk_i32 s0, 0x3000
	s_mov_b32 s20, 0xbfb8aa3b
	s_movk_i32 s93, 0x110
	v_readlane_b32 s37, v253, 49
	v_readlane_b32 s38, v253, 50
	v_readlane_b32 s39, v253, 51
	v_readlane_b32 s40, v253, 52
	v_readlane_b32 s41, v253, 53
	v_readlane_b32 s46, v253, 58
	v_readlane_b32 s47, v253, 59
	v_readlane_b32 s48, v253, 60
	v_readlane_b32 s49, v253, 61
	v_readlane_b32 s50, v253, 62
	v_readlane_b32 s51, v253, 63
	global_load_dwordx4 v[70:73], v68, s[22:23] offset:16
	global_load_dwordx4 v[74:77], v68, s[22:23]
	global_load_dwordx4 v[114:117], v68, s[6:7] offset:16
	global_load_dwordx4 v[118:121], v68, s[6:7]
	global_load_dwordx4 v[122:125], v68, s[6:7] offset:1040
	global_load_dwordx4 v[126:129], v68, s[6:7] offset:1024
	global_load_dwordx4 v[130:133], v68, s[6:7] offset:2064
	global_load_dwordx4 v[134:137], v68, s[6:7] offset:2048
	global_load_dwordx4 v[138:141], v68, s[6:7] offset:3088
	global_load_dwordx4 v[142:145], v68, s[6:7] offset:3072
	global_load_dwordx4 v[146:149], v69, s[6:7] offset:16
	global_load_dwordx4 v[150:153], v69, s[6:7]
	global_load_dwordx4 v[154:157], v69, s[6:7] offset:1040
	global_load_dwordx4 v[158:161], v69, s[6:7] offset:1024
	global_load_dwordx4 v[162:165], v69, s[6:7] offset:2064
	global_load_dwordx4 v[166:169], v69, s[6:7] offset:2048
	global_load_dwordx4 v[170:173], v69, s[6:7] offset:3088
	global_load_dwordx4 v[174:177], v69, s[6:7] offset:3072
	global_load_dwordx4 v[178:181], v94, s[6:7] offset:16
	global_load_dwordx4 v[182:185], v94, s[6:7]
	global_load_dwordx4 v[186:189], v94, s[6:7] offset:1040
	global_load_dwordx4 v[190:193], v94, s[6:7] offset:1024
	global_load_dwordx4 v[202:205], v94, s[6:7] offset:2064
	global_load_dwordx4 v[206:209], v94, s[6:7] offset:2048
	global_load_dwordx4 v[210:213], v94, s[6:7] offset:3088
	global_load_dwordx4 v[214:217], v94, s[6:7] offset:3072
	global_load_dwordx4 v[218:221], v95, s[6:7] offset:16
	global_load_dwordx4 v[222:225], v95, s[6:7]
	global_load_dwordx4 v[226:229], v95, s[6:7] offset:1040
	global_load_dwordx4 v[230:233], v95, s[6:7] offset:1024
	global_load_dwordx4 v[78:81], v95, s[6:7] offset:2064
	global_load_dwordx4 v[82:85], v95, s[6:7] offset:2048
	global_load_dwordx4 v[86:89], v95, s[6:7] offset:3088
	global_load_dwordx4 v[90:93], v95, s[6:7] offset:3072
	s_waitcnt vmcnt(0) lgkmcnt(0)
; __device__ __forceinline__ float logsigmoid_(float z) { return fminf(z, 0.f) - __logf(1.f + __expf(-fabsf(z))); }
; template <int TYPE>
; __device__ __forceinline__ void lg_compute(const KArgs& a, unsigned char* wsb, int l, int h, int dir, const LgRaw& raw, LAS unsigned char* lds, int tid) {
;     ...
;         f32x4 z0 = *(const f32x4*)bs, z1 = *(const f32x4*)(bs + 4);
; #pragma unroll
;         for (int r = 0; r < 16; ++r) { z0 += ua[r] * *(const f32x4*)(up + r * 256); z1 += ua[r] * *(const f32x4*)(up + r * 256 + 4); }
;         f32x4 g0, g1;
; #pragma unroll
;         for (int e = 0; e < 4; ++e) { g0[e] = logsigmoid_(z0[e]) * (1.f / 16.f); g1[e] = logsigmoid_(z1[e]) * (1.f / 16.f); }
	v_lshlrev_b32_e32 v30, 16, v14
	v_and_b32_e32 v32, 0xffff0000, v14
	v_lshlrev_b32_e32 v34, 16, v15
	v_and_b32_e32 v36, 0xffff0000, v15
	v_lshlrev_b32_e32 v38, 16, v16
	v_and_b32_e32 v40, 0xffff0000, v16
	v_lshlrev_b32_e32 v42, 16, v17
	v_and_b32_e32 v44, 0xffff0000, v17
	v_lshlrev_b32_e32 v10, 2, v13
	v_mov_b32_e32 v11, v113
	v_lshlrev_b32_e32 v46, 16, v64
	v_and_b32_e32 v48, 0xffff0000, v64
	v_lshlrev_b32_e32 v50, 16, v65
	v_and_b32_e32 v52, 0xffff0000, v65
	v_lshlrev_b32_e32 v54, 16, v66
	v_and_b32_e32 v56, 0xffff0000, v66
	v_lshlrev_b32_e32 v58, 16, v67
	v_and_b32_e32 v60, 0xffff0000, v67
	v_pk_fma_f32 v[22:23], v[30:31], v[114:115], v[70:71] op_sel_hi:[0,1,1]
	v_pk_fma_f32 v[24:25], v[30:31], v[116:117], v[72:73] op_sel_hi:[0,1,1]
	v_pk_fma_f32 v[26:27], v[30:31], v[118:119], v[74:75] op_sel_hi:[0,1,1]
	v_pk_fma_f32 v[28:29], v[30:31], v[120:121], v[76:77] op_sel_hi:[0,1,1]
	v_pk_fma_f32 v[22:23], v[32:33], v[122:123], v[22:23] op_sel_hi:[0,1,1]
	v_pk_fma_f32 v[24:25], v[32:33], v[124:125], v[24:25] op_sel_hi:[0,1,1]
	v_pk_fma_f32 v[26:27], v[32:33], v[126:127], v[26:27] op_sel_hi:[0,1,1]
	v_pk_fma_f32 v[28:29], v[32:33], v[128:129], v[28:29] op_sel_hi:[0,1,1]
	v_pk_fma_f32 v[22:23], v[34:35], v[130:131], v[22:23] op_sel_hi:[0,1,1]
	v_pk_fma_f32 v[24:25], v[34:35], v[132:133], v[24:25] op_sel_hi:[0,1,1]
	v_pk_fma_f32 v[26:27], v[34:35], v[134:135], v[26:27] op_sel_hi:[0,1,1]
	v_pk_fma_f32 v[28:29], v[34:35], v[136:137], v[28:29] op_sel_hi:[0,1,1]
	v_pk_fma_f32 v[22:23], v[36:37], v[138:139], v[22:23] op_sel_hi:[0,1,1]
	v_pk_fma_f32 v[24:25], v[36:37], v[140:141], v[24:25] op_sel_hi:[0,1,1]
	v_pk_fma_f32 v[26:27], v[36:37], v[142:143], v[26:27] op_sel_hi:[0,1,1]
	v_pk_fma_f32 v[28:29], v[36:37], v[144:145], v[28:29] op_sel_hi:[0,1,1]
	v_pk_fma_f32 v[22:23], v[38:39], v[146:147], v[22:23] op_sel_hi:[0,1,1]
	v_pk_fma_f32 v[24:25], v[38:39], v[148:149], v[24:25] op_sel_hi:[0,1,1]
	v_pk_fma_f32 v[26:27], v[38:39], v[150:151], v[26:27] op_sel_hi:[0,1,1]
	v_pk_fma_f32 v[28:29], v[38:39], v[152:153], v[28:29] op_sel_hi:[0,1,1]
	v_pk_fma_f32 v[22:23], v[40:41], v[154:155], v[22:23] op_sel_hi:[0,1,1]
	v_pk_fma_f32 v[24:25], v[40:41], v[156:157], v[24:25] op_sel_hi:[0,1,1]
	v_pk_fma_f32 v[26:27], v[40:41], v[158:159], v[26:27] op_sel_hi:[0,1,1]
	v_pk_fma_f32 v[28:29], v[40:41], v[160:161], v[28:29] op_sel_hi:[0,1,1]
	v_pk_fma_f32 v[22:23], v[42:43], v[162:163], v[22:23] op_sel_hi:[0,1,1]
	v_pk_fma_f32 v[24:25], v[42:43], v[164:165], v[24:25] op_sel_hi:[0,1,1]
	v_pk_fma_f32 v[26:27], v[42:43], v[166:167], v[26:27] op_sel_hi:[0,1,1]
	v_pk_fma_f32 v[28:29], v[42:43], v[168:169], v[28:29] op_sel_hi:[0,1,1]
	v_pk_fma_f32 v[22:23], v[44:45], v[170:171], v[22:23] op_sel_hi:[0,1,1]
	v_pk_fma_f32 v[24:25], v[44:45], v[172:173], v[24:25] op_sel_hi:[0,1,1]
	v_pk_fma_f32 v[26:27], v[44:45], v[174:175], v[26:27] op_sel_hi:[0,1,1]
	v_pk_fma_f32 v[28:29], v[44:45], v[176:177], v[28:29] op_sel_hi:[0,1,1]
	v_pk_fma_f32 v[22:23], v[46:47], v[178:179], v[22:23] op_sel_hi:[0,1,1]
	v_pk_fma_f32 v[24:25], v[46:47], v[180:181], v[24:25] op_sel_hi:[0,1,1]
	v_pk_fma_f32 v[26:27], v[46:47], v[182:183], v[26:27] op_sel_hi:[0,1,1]
	v_pk_fma_f32 v[28:29], v[46:47], v[184:185], v[28:29] op_sel_hi:[0,1,1]
	v_pk_fma_f32 v[22:23], v[48:49], v[186:187], v[22:23] op_sel_hi:[0,1,1]
	v_pk_fma_f32 v[24:25], v[48:49], v[188:189], v[24:25] op_sel_hi:[0,1,1]
	v_pk_fma_f32 v[26:27], v[48:49], v[190:191], v[26:27] op_sel_hi:[0,1,1]
	v_pk_fma_f32 v[28:29], v[48:49], v[192:193], v[28:29] op_sel_hi:[0,1,1]
	v_pk_fma_f32 v[22:23], v[50:51], v[202:203], v[22:23] op_sel_hi:[0,1,1]
	v_pk_fma_f32 v[24:25], v[50:51], v[204:205], v[24:25] op_sel_hi:[0,1,1]
	v_pk_fma_f32 v[26:27], v[50:51], v[206:207], v[26:27] op_sel_hi:[0,1,1]
	v_pk_fma_f32 v[28:29], v[50:51], v[208:209], v[28:29] op_sel_hi:[0,1,1]
	v_pk_fma_f32 v[22:23], v[52:53], v[210:211], v[22:23] op_sel_hi:[0,1,1]
	v_pk_fma_f32 v[24:25], v[52:53], v[212:213], v[24:25] op_sel_hi:[0,1,1]
	v_pk_fma_f32 v[26:27], v[52:53], v[214:215], v[26:27] op_sel_hi:[0,1,1]
	v_pk_fma_f32 v[28:29], v[52:53], v[216:217], v[28:29] op_sel_hi:[0,1,1]
	v_pk_fma_f32 v[22:23], v[54:55], v[218:219], v[22:23] op_sel_hi:[0,1,1]
	v_pk_fma_f32 v[24:25], v[54:55], v[220:221], v[24:25] op_sel_hi:[0,1,1]
	v_pk_fma_f32 v[26:27], v[54:55], v[222:223], v[26:27] op_sel_hi:[0,1,1]
	v_pk_fma_f32 v[28:29], v[54:55], v[224:225], v[28:29] op_sel_hi:[0,1,1]
	v_pk_fma_f32 v[22:23], v[56:57], v[226:227], v[22:23] op_sel_hi:[0,1,1]
	v_pk_fma_f32 v[24:25], v[56:57], v[228:229], v[24:25] op_sel_hi:[0,1,1]
	v_pk_fma_f32 v[26:27], v[56:57], v[230:231], v[26:27] op_sel_hi:[0,1,1]
	v_pk_fma_f32 v[28:29], v[56:57], v[232:233], v[28:29] op_sel_hi:[0,1,1]
	v_pk_fma_f32 v[22:23], v[58:59], v[78:79], v[22:23] op_sel_hi:[0,1,1]
	v_pk_fma_f32 v[24:25], v[58:59], v[80:81], v[24:25] op_sel_hi:[0,1,1]
	v_pk_fma_f32 v[26:27], v[58:59], v[82:83], v[26:27] op_sel_hi:[0,1,1]
	v_pk_fma_f32 v[28:29], v[58:59], v[84:85], v[28:29] op_sel_hi:[0,1,1]
	v_pk_fma_f32 v[14:15], v[60:61], v[90:91], v[26:27] op_sel_hi:[0,1,1]
	v_pk_fma_f32 v[16:17], v[60:61], v[92:93], v[28:29] op_sel_hi:[0,1,1]
	v_pk_fma_f32 v[18:19], v[60:61], v[86:87], v[22:23] op_sel_hi:[0,1,1]
	v_pk_fma_f32 v[20:21], v[60:61], v[88:89], v[24:25] op_sel_hi:[0,1,1]
	s_mov_b32 s0, 0x3d800000
	v_mul_f32_e64 v11, |v14|, s20
	v_exp_f32_e32 v11, v11
	v_min_f32_e32 v22, 0, v14
	v_add_f32_e32 v11, 1.0, v11
	v_min_f32_e32 v24, 0, v18
	v_min_f32_e32 v23, 0, v15
	v_log_f32_e32 v11, v11
	v_min_f32_e32 v25, 0, v19
	v_min_f32_e32 v26, 0, v16
	v_mul_f32_e32 v14, 0x3f317217, v11
	v_fma_f32 v14, v11, s92, -v14
	v_fmac_f32_e32 v14, 0x3377d1cf, v11
; #define LAS __attribute__((address_space(3)))
; __device__ __forceinline__ float logsigmoid_(float z) { return fminf(z, 0.f) - __logf(1.f + __expf(-fabsf(z))); }
; template <int TYPE>
; __device__ __forceinline__ void lg_compute(const KArgs& a, unsigned char* wsb, int l, int h, int dir, const LgRaw& raw, LAS unsigned char* lds, int tid) {
;     ...
;         for (int e = 0; e < 4; ++e) { g0[e] = logsigmoid_(z0[e]) * (1.f / 16.f); g1[e] = logsigmoid_(z1[e]) * (1.f / 16.f); }
;         *(LAS f32x4*)(G + i * C::LDG + d8 * 8) = g0; *(LAS f32x4*)(G + i * C::LDG + d8 * 8 + 4) = g1;
;         *(LAS bf16x8*)(Kb + i * C::LDK_ + d8 * 8) = raw.k;
;     }
; }
; template <int TYPE>
; __device__ __forceinline__ void cumsum_g(int dir, LAS unsigned char* lds, int tid) {
;     using C = Cfg<TYPE>; constexpr int NSEG = 512 / C::DK, SEGL = 64 / NSEG;
;     LAS float* G = (LAS float*)(lds + SC_G); LAS float* SG = (LAS float*)(lds + SC_SEG);
;     const int d = tid % C::DK, seg = tid / C::DK;
;     __syncthreads();
;     float run = 0.f;
; #pragma unroll
;     for (int ii = 0; ii < SEGL; ++ii) { const int i = seg * SEGL + (dir ? SEGL - 1 - ii : ii); run += G[i * C::LDG + d]; G[i * C::LDG + d] = run; }
;     SG[seg * 128 + d] = run;
;     __syncthreads();
;     float off = 0.f;
; #pragma unroll
;     for (int s = 0; s < NSEG; ++s) { const bool before = dir ? (s > seg) : (s < seg); if (before) off += SG[s * 128 + d]; }
; #pragma unroll
;     for (int ii = 0; ii < SEGL; ++ii) { const int i = seg * SEGL + ii; G[i * C::LDG + d] += off; }
;     __syncthreads();
; }
; __device__ __forceinline__ void vT_write(const VRaw& r, LAS unsigned char* lds, int tid) {
;     LAS bf16_t* VT = (LAS bf16_t*)(lds + SC_VT);
;     const int v8 = tid & 15;
; #pragma unroll
;     for (int e2 = 0; e2 < 2; ++e2) { const int i = (tid >> 4) + 32 * e2; const bf16x8 x = e2 ? r.x1 : r.x0; const int pc = ((((i >> 3) ^ (v8 & 7)) << 3) | (i & 7));
; #pragma unroll
;         for (int e = 0; e < 8; ++e) VT[(v8 * 8 + e) * LDT + pc] = (bf16_t)x[e]; }
	v_fmac_f32_e32 v14, 0x3f317217, v11
	v_min_f32_e32 v28, 0, v20
	v_min_f32_e32 v27, 0, v17
	v_mov_b32_e32 v11, v14
	v_mul_f32_e64 v11, |v18|, s20
	v_exp_f32_e32 v11, v11
	v_min_f32_e32 v29, 0, v21
	v_add_f32_e32 v11, 1.0, v11
	s_nop 1
	v_log_f32_e32 v11, v11
	s_nop 0
	v_mul_f32_e32 v18, 0x3f317217, v11
	v_fma_f32 v18, v11, s92, -v18
	v_fmac_f32_e32 v18, 0x3377d1cf, v11
	v_fmac_f32_e32 v18, 0x3f317217, v11
	s_nop 1
	v_mov_b32_e32 v11, v18
	v_mul_f32_e64 v11, |v15|, s20
	v_exp_f32_e32 v11, v11
	s_nop 0
	v_add_f32_e32 v11, 1.0, v11
	s_nop 1
	v_log_f32_e32 v11, v11
	s_nop 0
	v_mul_f32_e32 v15, 0x3f317217, v11
	v_fma_f32 v15, v11, s92, -v15
	v_fmac_f32_e32 v15, 0x3377d1cf, v11
	v_fmac_f32_e32 v15, 0x3f317217, v11
	s_nop 1
	v_mov_b32_e32 v11, v15
	v_mul_f32_e64 v11, |v19|, s20
	v_exp_f32_e32 v11, v11
	v_pk_add_f32 v[14:15], v[22:23], v[14:15] neg_lo:[0,1] neg_hi:[0,1]
	v_add_f32_e32 v11, 1.0, v11
	v_pk_mul_f32 v[14:15], v[14:15], s[0:1] op_sel_hi:[1,0]
	s_nop 0
	v_log_f32_e32 v11, v11
	s_nop 0
	v_mul_f32_e32 v19, 0x3f317217, v11
	v_fma_f32 v19, v11, s92, -v19
	v_fmac_f32_e32 v19, 0x3377d1cf, v11
	v_fmac_f32_e32 v19, 0x3f317217, v11
	s_nop 1
	v_mov_b32_e32 v11, v19
	v_mul_f32_e64 v11, |v16|, s20
	v_exp_f32_e32 v11, v11
	v_pk_add_f32 v[18:19], v[24:25], v[18:19] neg_lo:[0,1] neg_hi:[0,1]
	global_load_dwordx4 v[22:25], v[4:5], off offset:1024
	s_nop 0
	global_load_dwordx4 v[4:7], v[6:7], off offset:1024
	v_pk_mul_f32 v[18:19], v[18:19], s[0:1] op_sel_hi:[1,0]
	v_add_f32_e32 v11, 1.0, v11
	s_nop 1
	v_log_f32_e32 v11, v11
	s_nop 0
	v_mul_f32_e32 v16, 0x3f317217, v11
	v_fma_f32 v16, v11, s92, -v16
	v_fmac_f32_e32 v16, 0x3377d1cf, v11
	v_fmac_f32_e32 v16, 0x3f317217, v11
	s_nop 1
	v_mov_b32_e32 v11, v16
	v_mul_f32_e64 v11, |v20|, s20
	v_exp_f32_e32 v11, v11
	s_nop 0
	v_add_f32_e32 v11, 1.0, v11
	s_nop 1
	v_log_f32_e32 v11, v11
	s_nop 0
	v_mul_f32_e32 v20, 0x3f317217, v11
	v_fma_f32 v20, v11, s92, -v20
	v_fmac_f32_e32 v20, 0x3377d1cf, v11
	v_fmac_f32_e32 v20, 0x3f317217, v11
	s_nop 1
	v_mov_b32_e32 v11, v20
	v_mul_f32_e64 v11, |v17|, s20
	v_exp_f32_e32 v11, v11
	s_nop 0
	v_add_f32_e32 v11, 1.0, v11
	s_nop 1
	v_log_f32_e32 v11, v11
	s_nop 0
	v_mul_f32_e32 v17, 0x3f317217, v11
	v_fma_f32 v17, v11, s92, -v17
	v_fmac_f32_e32 v17, 0x3377d1cf, v11
	v_fmac_f32_e32 v17, 0x3f317217, v11
	s_nop 1
	v_mov_b32_e32 v11, v17
	v_mul_f32_e64 v11, |v21|, s20
	v_exp_f32_e32 v11, v11
	v_pk_add_f32 v[16:17], v[26:27], v[16:17] neg_lo:[0,1] neg_hi:[0,1]
	v_add_f32_e32 v11, 1.0, v11
	v_pk_mul_f32 v[16:17], v[16:17], s[0:1] op_sel_hi:[1,0]
	s_nop 0
	v_log_f32_e32 v11, v11
	s_nop 0
	v_mul_f32_e32 v21, 0x3f317217, v11
	v_fma_f32 v21, v11, s92, -v21
	v_fmac_f32_e32 v21, 0x3377d1cf, v11
	v_fmac_f32_e32 v21, 0x3f317217, v11
	s_nop 1
	v_mov_b32_e32 v11, v21
	s_movk_i32 s6, 0x110
	v_mul_lo_u32 v11, v8, s6
	v_add_u32_e32 v11, 0, v11
	v_pk_add_f32 v[20:21], v[28:29], v[20:21] neg_lo:[0,1] neg_hi:[0,1]
	v_add_u32_e32 v10, v11, v10
	v_pk_mul_f32 v[20:21], v[20:21], s[0:1] op_sel_hi:[1,0]
	ds_write_b128 v10, v[14:17]
	ds_write_b128 v10, v[18:21] offset:16
	v_lshlrev_b32_e32 v10, 7, v8
	v_sub_u32_e32 v10, v11, v10
	v_add_u32_e32 v10, v10, v112
	ds_write_b128 v10, v[0:3] offset:33792
	v_and_b32_e32 v1, -8, v35
	v_lshlrev_b32_e32 v0, 1, v35
	v_add_u32_e32 v1, 32, v1
	v_and_b32_e32 v0, 14, v0
	v_bitop3_b32 v2, v35, v13, -8 bitop3:0x6c
	v_bitop3_b32 v1, v1, v9, 56 bitop3:0x78
	v_add_u32_e32 v0, s95, v0
	v_lshlrev_b32_e32 v2, 1, v2
	v_mul_u32_u24_e32 v3, 0x90, v37
	v_lshlrev_b32_e32 v1, 1, v1
	v_add3_u32 v2, v0, v2, v3
	v_add3_u32 v0, v0, v1, v3
	s_waitcnt vmcnt(0) lgkmcnt(0)
	ds_write_b16 v2, v22
	ds_write_b16_d16_hi v2, v22 offset:144
	ds_write_b16 v2, v23 offset:288
	ds_write_b16_d16_hi v2, v23 offset:432
	ds_write_b16 v2, v24 offset:576
	ds_write_b16_d16_hi v2, v24 offset:720
	ds_write_b16 v2, v25 offset:864
	ds_write_b16_d16_hi v2, v25 offset:1008
	ds_write_b16 v0, v4
	ds_write_b16_d16_hi v0, v4 offset:144
	ds_write_b16 v0, v5 offset:288
	ds_write_b16_d16_hi v0, v5 offset:432
	ds_write_b16 v0, v6 offset:576
	ds_write_b16_d16_hi v0, v6 offset:720
	ds_write_b16 v0, v7 offset:864
	ds_write_b16_d16_hi v0, v7 offset:1008
	v_ashrrev_i32_e32 v0, 31, v12
	v_lshrrev_b32_e32 v0, 26, v0
	v_add_u32_e32 v0, v12, v0
	v_ashrrev_i32_e32 v1, 6, v0
	v_and_b32_e32 v0, 0x3fffffc0, v0
	v_sub_u32_e32 v0, v12, v0
	v_lshlrev_b32_e32 v4, 3, v1
	v_lshlrev_b32_e32 v5, 2, v0
	v_add_u32_e32 v0, 0, v5
	v_and_or_b32 v2, s18, 7, v4
	v_mad_u64_u32 v[2:3], s[4:5], v2, s6, v[0:1]
	s_waitcnt lgkmcnt(0)
	s_barrier
	ds_read_b32 v80, v2
	s_cselect_b32 s4, 1, 6
	s_movk_i32 s0, 0xffc1
	v_or_b32_e32 v64, s4, v4
	v_mad_u64_u32 v[64:65], s[4:5], v64, s6, v[0:1]
	ds_read_b32 v81, v64
	s_cselect_b32 s4, 2, 5
	v_or_b32_e32 v66, s4, v4
	v_mad_u64_u32 v[66:67], s[4:5], v66, s6, v[0:1]
	ds_read_b32 v82, v66
	v_or_b32_e32 v68, s19, v4
	v_mad_u64_u32 v[68:69], s[4:5], v68, s6, v[0:1]
	ds_read_b32 v83, v68
	v_subrev_u32_e32 v70, s17, v4
	v_mad_u64_u32 v[70:71], s[4:5], v70, s6, v[0:1]
	ds_read_b32 v84, v70 offset:1088
	s_cselect_b32 s4, 5, 2
	v_or_b32_e32 v72, s4, v4
	v_mad_u64_u32 v[72:73], s[4:5], v72, s6, v[0:1]
	ds_read_b32 v85, v72
	s_cselect_b32 s4, 6, 1
	v_or_b32_e32 v74, s4, v4
	v_mad_u64_u32 v[74:75], s[4:5], v74, s6, v[0:1]
	ds_read_b32 v86, v74
	s_cselect_b32 s4, 7, 0
	v_or_b32_e32 v76, s4, v4
	v_mad_u64_u32 v[76:77], s[4:5], v76, s6, v[0:1]
	ds_read_b32 v87, v76
	v_cmp_gt_i32_e64 s[4:5], s0, v12
	v_cmp_lt_i32_e64 s[6:7], 63, v12
	s_waitcnt lgkmcnt(0)
	v_add_f32_e32 v6, 0, v80
	ds_write_b32 v2, v6
	v_add_f32_e32 v6, v6, v81
	ds_write_b32 v64, v6
	v_add_f32_e32 v6, v6, v82
	ds_write_b32 v66, v6
	v_add_f32_e32 v6, v6, v83
	ds_write_b32 v68, v6
	v_add_f32_e32 v6, v6, v84
	ds_write_b32 v70, v6 offset:1088
	v_add_f32_e32 v6, v6, v85
	ds_write_b32 v72, v6
	v_add_f32_e32 v6, v6, v86
	ds_write_b32 v74, v6
	v_add_f32_e32 v3, v6, v87
	ds_write_b32 v76, v3


; template <int TYPE>
; __device__ __forceinline__ void cumsum_g(int dir, LAS unsigned char* lds, int tid) {
;     ...
;     SG[seg * 128 + d] = run;
;     __syncthreads();
;     float off = 0.f;
; #pragma unroll
;     for (int s = 0; s < NSEG; ++s) { const bool before = dir ? (s > seg) : (s < seg); if (before) off += SG[s * 128 + d]; }
	v_add_u32_e32 v2, s74, v5
	v_lshl_add_u32 v4, v1, 9, v2
	ds_write_b32 v4, v3
	v_cndmask_b32_e64 v3, 0, 1, s[6:7]
	v_cndmask_b32_e64 v4, 0, 1, s[4:5]
	v_cndmask_b32_e32 v3, v4, v3, vcc
	v_and_b32_e32 v3, 1, v3
	v_cmp_eq_u32_e64 s[4:5], 1, v3
	v_mov_b32_e32 v3, 0
	s_waitcnt lgkmcnt(0)
	s_barrier
	s_and_saveexec_b64 s[6:7], s[4:5]
	s_cbranch_execz .LBB0_290
	ds_read_b32 v3, v2
	s_waitcnt lgkmcnt(0)
	v_add_f32_e32 v3, 0, v3

; #define LAS __attribute__((address_space(3)))
; __device__ __forceinline__ float sigmoid_(float z) { return __builtin_amdgcn_rcpf(1.f + __expf(-z)); }
; template <int TYPE>
; __device__ __forceinline__ void lg_compute(const KArgs& a, unsigned char* wsb, int l, int h, int dir, const LgRaw& raw, LAS unsigned char* lds, int tid) {
;     ...
;         const float* lbp = (const float*)(wsb + WS_LB) + (dir * DEPTH + l) * 512 + h * 128;
;         const int d8 = tid & 15;
;         const f32x4 lb0 = *(const f32x4*)(lbp + d8 * 8), lb1 = *(const f32x4*)(lbp + d8 * 8 + 4);
;         const float lb[8] = {lb0[0], lb0[1], lb0[2], lb0[3], lb1[0], lb1[1], lb1[2], lb1[3]};
; #pragma unroll
;         for (int e2 = 0; e2 < 2; ++e2) { const int i = (tid >> 4) + 32 * e2;
;             float z[8], lg[8], kk[8]; unpack8(e2 ? raw.a1 : raw.a0, z);
; #pragma unroll
;             for (int e = 0; e < 8; ++e) { const float sg = sigmoid_(fmaxf(z[e], -80.f)); lg[e] = __logf(lb[e] + (1.f - lb[e]) * sg); kk[e] = (1.f - lb[e]) * (1.f - sg); }
;             *(LAS f32x4*)(G + i * C::LDG + d8 * 8) = (f32x4){lg[0], lg[1], lg[2], lg[3]}; *(LAS f32x4*)(G + i * C::LDG + d8 * 8 + 4) = (f32x4){lg[4], lg[5], lg[6], lg[7]};
;             *(LAS bf16x8*)(Kb + i * C::LDK_ + d8 * 8) = pack8(kk); }
.LBB0_498:
	s_lshl_b32 s54, s54, 10
	s_or_b32 s72, s54, s56
	v_lshl_add_u64 v[48:49], s[72:73], 2, v[86:87]
	global_load_dwordx4 v[52:55], v[48:49], off
	s_nop 0
	global_load_dwordx4 v[48:51], v[48:49], off offset:16
	v_lshlrev_b32_e32 v92, 16, v60
	v_lshlrev_b32_e32 v101, 16, v61
	v_and_b32_e32 v102, 0xffff0000, v61
	v_max_f32_e32 v61, v92, v92
	v_max_f32_e32 v61, 0xc2a00000, v61
	v_mul_f32_e32 v61, 0xbfb8aa3b, v61
	v_and_b32_e32 v60, 0xffff0000, v60
	v_exp_f32_e32 v61, v61
	v_max_f32_e32 v60, v60, v60
	v_max_f32_e32 v60, 0xc2a00000, v60
	v_mul_f32_e32 v60, 0xbfb8aa3b, v60
	v_add_f32_e32 v61, 1.0, v61
	v_exp_f32_e32 v60, v60
	v_lshlrev_b32_e32 v131, 16, v62
	v_and_b32_e32 v100, 0xffff0000, v62
	v_rcp_f32_e32 v62, v61
	v_add_f32_e32 v60, 1.0, v60
	v_lshlrev_b32_e32 v99, 16, v63
	v_and_b32_e32 v98, 0xffff0000, v63
	v_rcp_f32_e32 v63, v60
	v_max_f32_e32 v100, v100, v100
	v_max_f32_e32 v100, 0xc2a00000, v100
	v_mul_f32_e32 v100, 0xbfb8aa3b, v100
	v_pk_add_f32 v[94:95], v[62:63], 1.0 op_sel_hi:[1,0] neg_lo:[1,0] neg_hi:[1,0]
	v_exp_f32_e32 v100, v100
	v_max_f32_e32 v99, v99, v99
	v_max_f32_e32 v99, 0xc2a00000, v99
	v_mul_f32_e32 v99, 0xbfb8aa3b, v99
	v_add_f32_e32 v100, 1.0, v100
	v_rcp_f32_e32 v135, v100
	v_exp_f32_e32 v99, v99
	v_max_f32_e32 v98, v98, v98
	v_max_f32_e32 v98, 0xc2a00000, v98
	v_mul_f32_e32 v98, 0xbfb8aa3b, v98
	v_exp_f32_e32 v98, v98
	v_add_f32_e32 v99, 1.0, v99
	v_rcp_f32_e32 v138, v99
	v_add_f32_e32 v98, 1.0, v98
	v_rcp_f32_e32 v139, v98
	s_waitcnt vmcnt(0) lgkmcnt(0)
	v_pk_add_f32 v[92:93], v[52:53], 1.0 op_sel_hi:[1,0] neg_lo:[1,0] neg_hi:[1,0]
	s_nop 0
	v_fma_f32 v60, v92, v62, v52
	v_pk_mul_f32 v[96:97], v[92:93], v[94:95]
	v_pk_add_f32 v[94:95], v[54:55], 1.0 op_sel_hi:[1,0] neg_lo:[1,0] neg_hi:[1,0]
	v_log_f32_e32 v60, v60
	v_pk_add_f32 v[98:99], v[50:51], 1.0 op_sel_hi:[1,0] neg_lo:[1,0] neg_hi:[1,0]
	v_pk_add_f32 v[140:141], v[138:139], 1.0 op_sel_hi:[1,0] neg_lo:[1,0] neg_hi:[1,0]
	v_mul_f32_e32 v61, 0x3f317217, v60
	v_fma_f32 v61, v60, s92, -v61
	v_fmac_f32_e32 v61, 0x3377d1cf, v60
	v_fmac_f32_e32 v61, 0x3f317217, v60
	v_pk_mul_f32 v[140:141], v[98:99], v[140:141]
	s_nop 0
	v_mov_b32_e32 v60, v61
	v_fma_f32 v61, v93, v63, v53
	s_nop 1
	v_log_f32_e32 v61, v61
	s_nop 0
	v_mul_f32_e32 v62, 0x3f317217, v61
	v_fma_f32 v62, v61, s92, -v62
	v_fmac_f32_e32 v62, 0x3377d1cf, v61
	v_fmac_f32_e32 v62, 0x3f317217, v61
	s_nop 1
	v_mov_b32_e32 v61, v62
	v_max_f32_e32 v62, v101, v101
	v_max_f32_e32 v62, 0xc2a00000, v62
	v_mul_f32_e32 v62, 0xbfb8aa3b, v62
	v_exp_f32_e32 v62, v62
	s_nop 0
	v_add_f32_e32 v62, 1.0, v62
	v_rcp_f32_e32 v132, v62
	v_max_f32_e32 v62, v102, v102
	v_max_f32_e32 v62, 0xc2a00000, v62
	v_mul_f32_e32 v62, 0xbfb8aa3b, v62
	v_exp_f32_e32 v62, v62
	s_nop 0
	v_add_f32_e32 v62, 1.0, v62
	v_rcp_f32_e32 v133, v62
	v_fma_f32 v62, v94, v132, v54
	v_pk_add_f32 v[102:103], v[132:133], 1.0 op_sel_hi:[1,0] neg_lo:[1,0] neg_hi:[1,0]
	s_nop 0
	v_log_f32_e32 v62, v62
	v_pk_mul_f32 v[102:103], v[94:95], v[102:103]
	v_mul_f32_e32 v63, 0x3f317217, v62
	v_fma_f32 v63, v62, s92, -v63
	v_fmac_f32_e32 v63, 0x3377d1cf, v62
	v_fmac_f32_e32 v63, 0x3f317217, v62
	s_nop 1
	v_mov_b32_e32 v62, v63
	v_fma_f32 v63, v95, v133, v55
	s_nop 1
	v_log_f32_e32 v63, v63
	s_nop 0
	v_mul_f32_e32 v101, 0x3f317217, v63
	v_fma_f32 v101, v63, s92, -v101
	v_fmac_f32_e32 v101, 0x3377d1cf, v63
	v_fmac_f32_e32 v101, 0x3f317217, v63
	s_nop 1
	v_mov_b32_e32 v63, v101
	v_max_f32_e32 v101, v131, v131
	v_max_f32_e32 v101, 0xc2a00000, v101
	v_mul_f32_e32 v101, 0xbfb8aa3b, v101
	v_exp_f32_e32 v101, v101
	s_nop 0
	v_add_f32_e32 v101, 1.0, v101
	v_rcp_f32_e32 v134, v101
	v_pk_add_f32 v[100:101], v[48:49], 1.0 op_sel_hi:[1,0] neg_lo:[1,0] neg_hi:[1,0]
	v_pk_add_f32 v[136:137], v[134:135], 1.0 op_sel_hi:[1,0] neg_lo:[1,0] neg_hi:[1,0]
	v_fma_f32 v131, v100, v134, v48
	v_pk_mul_f32 v[136:137], v[100:101], v[136:137]
	s_nop 0
	v_log_f32_e32 v131, v131
	s_nop 0
	v_mul_f32_e32 v132, 0x3f317217, v131
	v_fma_f32 v132, v131, s92, -v132
	v_fmac_f32_e32 v132, 0x3377d1cf, v131
	v_fmac_f32_e32 v132, 0x3f317217, v131
	s_nop 1
	v_mov_b32_e32 v131, v132
	v_fma_f32 v131, v101, v135, v49
	s_nop 1
	v_log_f32_e32 v131, v131
	s_nop 0
	v_mul_f32_e32 v133, 0x3f317217, v131
	v_fma_f32 v133, v131, s92, -v133
	v_fmac_f32_e32 v133, 0x3377d1cf, v131
	v_fmac_f32_e32 v133, 0x3f317217, v131
	s_nop 1
	v_mov_b32_e32 v131, v133
	v_fma_f32 v131, v98, v138, v50
	s_nop 1
	v_log_f32_e32 v131, v131
	s_nop 0
	v_mul_f32_e32 v134, 0x3f317217, v131
	v_fma_f32 v134, v131, s92, -v134
	v_fmac_f32_e32 v134, 0x3377d1cf, v131
	v_fmac_f32_e32 v134, 0x3f317217, v131
	s_nop 1
	v_mov_b32_e32 v131, v134
	v_fma_f32 v131, v99, v139, v51
	s_nop 1
	v_log_f32_e32 v131, v131
	s_nop 0
	v_mul_f32_e32 v135, 0x3f317217, v131
	v_fma_f32 v135, v131, s92, -v135
	v_fmac_f32_e32 v135, 0x3377d1cf, v131
	v_fmac_f32_e32 v135, 0x3f317217, v131
	s_nop 1
	v_mov_b32_e32 v131, v135
	ds_write_b128 v125, v[60:63]
	ds_write_b128 v125, v[132:135] offset:16
	v_cvt_pk_bf16_f32 v60, v96, v97
	v_cvt_pk_bf16_f32 v61, v102, v103
	v_cvt_pk_bf16_f32 v62, v136, v137
	v_cvt_pk_bf16_f32 v63, v140, v141
	ds_write_b128 v126, v[60:63] offset:33792
	v_lshlrev_b32_e32 v62, 16, v56
	v_and_b32_e32 v63, 0xffff0000, v56
	v_max_f32_e32 v56, v62, v62
	v_max_f32_e32 v56, 0xc2a00000, v56
	v_mul_f32_e32 v56, 0xbfb8aa3b, v56
	v_exp_f32_e32 v56, v56
	v_lshlrev_b32_e32 v96, 16, v57
	v_and_b32_e32 v97, 0xffff0000, v57
	v_lshlrev_b32_e32 v102, 16, v58
	v_add_f32_e32 v56, 1.0, v56
	v_rcp_f32_e32 v56, v56
	v_and_b32_e32 v103, 0xffff0000, v58
	v_lshlrev_b32_e32 v61, 16, v59
	v_and_b32_e32 v60, 0xffff0000, v59
	v_fma_f32 v52, v92, v56, v52
	v_max_f32_e32 v61, v61, v61
; #define LAS __attribute__((address_space(3)))
; __device__ __forceinline__ float sigmoid_(float z) { return __builtin_amdgcn_rcpf(1.f + __expf(-z)); }
; template <int TYPE>
; __device__ __forceinline__ void lg_compute(const KArgs& a, unsigned char* wsb, int l, int h, int dir, const LgRaw& raw, LAS unsigned char* lds, int tid) {
;     ...
;         for (int e2 = 0; e2 < 2; ++e2) { const int i = (tid >> 4) + 32 * e2;
;             float z[8], lg[8], kk[8]; unpack8(e2 ? raw.a1 : raw.a0, z);
; #pragma unroll
;             for (int e = 0; e < 8; ++e) { const float sg = sigmoid_(fmaxf(z[e], -80.f)); lg[e] = __logf(lb[e] + (1.f - lb[e]) * sg); kk[e] = (1.f - lb[e]) * (1.f - sg); }
;             *(LAS f32x4*)(G + i * C::LDG + d8 * 8) = (f32x4){lg[0], lg[1], lg[2], lg[3]}; *(LAS f32x4*)(G + i * C::LDG + d8 * 8 + 4) = (f32x4){lg[4], lg[5], lg[6], lg[7]};
;             *(LAS bf16x8*)(Kb + i * C::LDK_ + d8 * 8) = pack8(kk); }
; template <int TYPE>
; __device__ __forceinline__ void cumsum_g(int dir, LAS unsigned char* lds, int tid) {
;     ...
;     __syncthreads();
;     float run = 0.f;
; #pragma unroll
;     for (int ii = 0; ii < SEGL; ++ii) { const int i = seg * SEGL + (dir ? SEGL - 1 - ii : ii); run += G[i * C::LDG + d]; G[i * C::LDG + d] = run; }
	v_max_f32_e32 v61, 0xc2a00000, v61
	v_log_f32_e32 v52, v52
	v_mul_f32_e32 v61, 0xbfb8aa3b, v61
	v_exp_f32_e32 v61, v61
	v_max_f32_e32 v60, v60, v60
	v_mul_f32_e32 v57, 0x3f317217, v52
	v_fma_f32 v57, v52, s92, -v57
	v_fmac_f32_e32 v57, 0x3377d1cf, v52
	v_fmac_f32_e32 v57, 0x3f317217, v52
	v_add_f32_e32 v61, 1.0, v61
	v_max_f32_e32 v60, 0xc2a00000, v60
	v_mov_b32_e32 v52, v57
	v_max_f32_e32 v57, v63, v63
	v_max_f32_e32 v57, 0xc2a00000, v57
	v_mul_f32_e32 v57, 0xbfb8aa3b, v57
	v_exp_f32_e32 v57, v57
	v_mul_f32_e32 v60, 0xbfb8aa3b, v60
	v_exp_f32_e32 v60, v60
	v_add_f32_e32 v57, 1.0, v57
	v_rcp_f32_e32 v57, v57
	v_add_f32_e32 v60, 1.0, v60
	v_fma_f32 v53, v93, v57, v53
	v_pk_add_f32 v[56:57], v[56:57], 1.0 op_sel_hi:[1,0] neg_lo:[1,0] neg_hi:[1,0]
	s_nop 0
	v_log_f32_e32 v53, v53
	v_pk_mul_f32 v[56:57], v[92:93], v[56:57]
	v_rcp_f32_e32 v93, v60
	v_mul_f32_e32 v58, 0x3f317217, v53
	v_fma_f32 v58, v53, s92, -v58
	v_fmac_f32_e32 v58, 0x3377d1cf, v53
	v_fmac_f32_e32 v58, 0x3f317217, v53
	v_fmac_f32_e32 v51, v99, v93
	s_nop 0
	v_mov_b32_e32 v53, v58
	v_max_f32_e32 v58, v96, v96
	v_max_f32_e32 v58, 0xc2a00000, v58
	v_mul_f32_e32 v58, 0xbfb8aa3b, v58
	v_exp_f32_e32 v58, v58
	s_nop 0
	v_add_f32_e32 v58, 1.0, v58
	v_rcp_f32_e32 v58, v58
	s_nop 0
	v_fma_f32 v54, v94, v58, v54
	s_nop 1
	v_log_f32_e32 v54, v54
	s_nop 0
	v_mul_f32_e32 v59, 0x3f317217, v54
	v_fma_f32 v59, v54, s92, -v59
	v_fmac_f32_e32 v59, 0x3377d1cf, v54
	v_fmac_f32_e32 v59, 0x3f317217, v54
	s_nop 1
	v_mov_b32_e32 v54, v59
	v_max_f32_e32 v59, v97, v97
	v_max_f32_e32 v59, 0xc2a00000, v59
	v_mul_f32_e32 v59, 0xbfb8aa3b, v59
	v_exp_f32_e32 v59, v59
	s_nop 0
	v_add_f32_e32 v59, 1.0, v59
	v_rcp_f32_e32 v59, v59
	s_nop 0
	v_fmac_f32_e32 v55, v95, v59
	v_pk_add_f32 v[58:59], v[58:59], 1.0 op_sel_hi:[1,0] neg_lo:[1,0] neg_hi:[1,0]
	s_nop 0
	v_log_f32_e32 v55, v55
	v_pk_mul_f32 v[58:59], v[94:95], v[58:59]
	v_mul_f32_e32 v62, 0x3f317217, v55
	v_fma_f32 v62, v55, s92, -v62
	v_fmac_f32_e32 v62, 0x3377d1cf, v55
	v_fmac_f32_e32 v62, 0x3f317217, v55
	s_nop 1
	v_mov_b32_e32 v55, v62
	v_max_f32_e32 v62, v102, v102
	v_max_f32_e32 v62, 0xc2a00000, v62
	v_mul_f32_e32 v62, 0xbfb8aa3b, v62
	v_exp_f32_e32 v62, v62
	s_nop 0
	v_add_f32_e32 v62, 1.0, v62
	v_rcp_f32_e32 v62, v62
	s_nop 0
	v_fma_f32 v48, v100, v62, v48
	s_nop 1
	v_log_f32_e32 v48, v48
	s_nop 0
	v_mul_f32_e32 v63, 0x3f317217, v48
	v_fma_f32 v63, v48, s92, -v63
	v_fmac_f32_e32 v63, 0x3377d1cf, v48
	v_fmac_f32_e32 v63, 0x3f317217, v48
	s_nop 1
	v_mov_b32_e32 v48, v63
	v_max_f32_e32 v63, v103, v103
	v_max_f32_e32 v63, 0xc2a00000, v63
	v_mul_f32_e32 v63, 0xbfb8aa3b, v63
	v_exp_f32_e32 v63, v63
	s_nop 0
	v_add_f32_e32 v63, 1.0, v63
	v_rcp_f32_e32 v63, v63
	s_nop 0
	v_fma_f32 v49, v101, v63, v49
	v_pk_add_f32 v[62:63], v[62:63], 1.0 op_sel_hi:[1,0] neg_lo:[1,0] neg_hi:[1,0]
	s_nop 0
	v_log_f32_e32 v49, v49
	v_pk_mul_f32 v[62:63], v[100:101], v[62:63]
	v_mul_f32_e32 v92, 0x3f317217, v49
	v_fma_f32 v92, v49, s92, -v92
	v_fmac_f32_e32 v92, 0x3377d1cf, v49
	v_fmac_f32_e32 v92, 0x3f317217, v49
	s_nop 1
	v_mov_b32_e32 v49, v92
	v_rcp_f32_e32 v92, v61
	s_nop 0
	v_fma_f32 v50, v98, v92, v50
	s_nop 1
	v_log_f32_e32 v50, v50
	s_nop 0
	v_mul_f32_e32 v61, 0x3f317217, v50
	v_fma_f32 v61, v50, s92, -v61
	v_fmac_f32_e32 v61, 0x3377d1cf, v50
	v_fmac_f32_e32 v61, 0x3f317217, v50
	s_nop 1
	v_mov_b32_e32 v50, v61
	s_nop 0
	v_log_f32_e32 v51, v51
	s_nop 0
	v_mul_f32_e32 v60, 0x3f317217, v51
	v_fma_f32 v60, v51, s92, -v60
	v_fmac_f32_e32 v60, 0x3377d1cf, v51
	v_fmac_f32_e32 v60, 0x3f317217, v51
	s_nop 1
	v_mov_b32_e32 v51, v60
	v_pk_add_f32 v[60:61], v[92:93], 1.0 op_sel_hi:[1,0] neg_lo:[1,0] neg_hi:[1,0]
	ds_write_b128 v125, v[52:55] offset:16896
	ds_write_b128 v125, v[48:51] offset:16912
	v_pk_mul_f32 v[60:61], v[98:99], v[60:61]
	v_cvt_pk_bf16_f32 v48, v56, v57
	v_cvt_pk_bf16_f32 v49, v58, v59
	v_cvt_pk_bf16_f32 v50, v62, v63
	v_cvt_pk_bf16_f32 v51, v60, v61
	ds_write_b128 v126, v[48:51] offset:42496
	v_or_b32_e32 v48, s95, v105
	v_mad_u64_u32 v[48:49], s[54:55], v48, s91, v[88:89]
	s_waitcnt lgkmcnt(0)
	s_barrier
	ds_read_b32 v174, v48
	v_or_b32_e32 v142, s87, v105
	v_mad_u64_u32 v[142:143], s[54:55], v142, s91, v[88:89]
	ds_read_b32 v175, v142
	v_or_b32_e32 v144, s86, v105
	v_mad_u64_u32 v[144:145], s[54:55], v144, s91, v[88:89]
	ds_read_b32 v176, v144
	v_or_b32_e32 v146, s85, v105
	v_mad_u64_u32 v[146:147], s[54:55], v146, s91, v[88:89]
	ds_read_b32 v177, v146
	v_or_b32_e32 v148, s84, v105
	v_mad_u64_u32 v[148:149], s[54:55], v148, s91, v[88:89]
	ds_read_b32 v178, v148
	v_or_b32_e32 v150, s83, v105
	v_mad_u64_u32 v[150:151], s[54:55], v150, s91, v[88:89]
	ds_read_b32 v179, v150
	v_or_b32_e32 v152, s82, v105
	v_mad_u64_u32 v[152:153], s[54:55], v152, s91, v[88:89]
	ds_read_b32 v180, v152
	v_or_b32_e32 v154, s81, v105
	v_mad_u64_u32 v[154:155], s[54:55], v154, s91, v[88:89]
	ds_read_b32 v181, v154
	v_or_b32_e32 v156, s77, v105
	v_mad_u64_u32 v[156:157], s[54:55], v156, s91, v[88:89]
	ds_read_b32 v182, v156
	v_or_b32_e32 v158, s80, v105
	v_mad_u64_u32 v[158:159], s[54:55], v158, s91, v[88:89]
	ds_read_b32 v183, v158
	v_or_b32_e32 v160, s79, v105
	v_mad_u64_u32 v[160:161], s[54:55], v160, s91, v[88:89]
	ds_read_b32 v184, v160
	v_or_b32_e32 v162, s78, v105
	v_mad_u64_u32 v[162:163], s[54:55], v162, s91, v[88:89]
	ds_read_b32 v185, v162
	v_or_b32_e32 v164, s76, v105
	v_mad_u64_u32 v[164:165], s[54:55], v164, s91, v[88:89]
	ds_read_b32 v186, v164
	v_or_b32_e32 v166, s75, v105
	v_mad_u64_u32 v[166:167], s[54:55], v166, s91, v[88:89]
	ds_read_b32 v187, v166
	v_or_b32_e32 v168, s74, v105
	v_mad_u64_u32 v[168:169], s[54:55], v168, s91, v[88:89]
	ds_read_b32 v188, v168
	v_or_b32_e32 v170, s71, v105
	v_mad_u64_u32 v[170:171], s[54:55], v170, s91, v[88:89]
	ds_read_b32 v189, v170
	s_waitcnt lgkmcnt(0)
	v_add_f32_e32 v50, 0, v174
	ds_write_b32 v48, v50
	v_add_f32_e32 v50, v50, v175
	ds_write_b32 v142, v50
	v_add_f32_e32 v50, v50, v176
	ds_write_b32 v144, v50
	v_add_f32_e32 v50, v50, v177
	ds_write_b32 v146, v50
	v_add_f32_e32 v50, v50, v178
	ds_write_b32 v148, v50
	v_add_f32_e32 v50, v50, v179
	ds_write_b32 v150, v50
	v_add_f32_e32 v50, v50, v180
	ds_write_b32 v152, v50
	v_add_f32_e32 v50, v50, v181
	ds_write_b32 v154, v50
	v_add_f32_e32 v50, v50, v182
	ds_write_b32 v156, v50
	v_add_f32_e32 v50, v50, v183
	ds_write_b32 v158, v50
	v_add_f32_e32 v50, v50, v184
	ds_write_b32 v160, v50
	v_add_f32_e32 v50, v50, v185
	ds_write_b32 v162, v50
	v_add_f32_e32 v50, v50, v186
	ds_write_b32 v164, v50
	v_add_f32_e32 v50, v50, v187
	ds_write_b32 v166, v50
	v_add_f32_e32 v50, v50, v188
	ds_write_b32 v168, v50
	v_add_f32_e32 v49, v50, v189
	ds_write_b32 v170, v49


; template <int TYPE>
; __device__ __forceinline__ void cumsum_g(int dir, LAS unsigned char* lds, int tid) {
;     ...
;     SG[seg * 128 + d] = run;
;     __syncthreads();
;     float off = 0.f;
; #pragma unroll
;     for (int s = 0; s < NSEG; ++s) { const bool before = dir ? (s > seg) : (s < seg); if (before) off += SG[s * 128 + d]; }
	ds_write_b32 v104, v49
	v_mov_b32_e32 v48, 0
	s_waitcnt lgkmcnt(0)
	s_barrier
	s_and_saveexec_b64 s[54:55], s[68:69]
	s_cbranch_execz .LBB0_500
	ds_read_b32 v48, v106
	s_waitcnt lgkmcnt(0)
	v_add_f32_e32 v48, 0, v48

; template <int TYPE>
; __device__ __forceinline__ void lg_compute(const KArgs& a, unsigned char* wsb, int l, int h, int dir, const LgRaw& raw, LAS unsigned char* lds, int tid) {
;     ...
;         float ua[16]; unpack8(raw.a0, ua); unpack8(raw.a1, ua + 8);
;         const float* up = (const float*)a.in[3] + (size_t)((l * 2 + dir) * 16) * 256 + h * 64 + d8 * 8;
;         const float* bs = (const float*)a.in[4] + (l * 2 + dir) * 256 + h * 64 + d8 * 8;
;         f32x4 z0 = *(const f32x4*)bs, z1 = *(const f32x4*)(bs + 4);
; #pragma unroll
;         for (int r = 0; r < 16; ++r) { z0 += ua[r] * *(const f32x4*)(up + r * 256); z1 += ua[r] * *(const f32x4*)(up + r * 256 + 4); }
.LBB0_515:
	s_or_b32 s70, s70, s5
	s_lshl_b32 s72, s70, 12
	v_lshlrev_b32_e32 v92, 16, v50
	v_and_b32_e32 v88, 0xffff0000, v50
	v_lshlrev_b32_e32 v86, 16, v51
	v_and_b32_e32 v84, 0xffff0000, v51
	v_lshl_add_u64 v[50:51], s[72:73], 2, v[70:71]
	s_lshl_b32 s72, s70, 8
	v_lshl_add_u64 v[120:121], s[72:73], 2, v[72:73]
	global_load_dwordx4 v[138:141], v[120:121], off offset:16
	global_load_dwordx4 v[142:145], v[120:121], off
	global_load_dwordx4 v[146:149], v[50:51], off offset:16
	global_load_dwordx4 v[150:153], v[50:51], off
	global_load_dwordx4 v[154:157], v[50:51], off offset:1040
	global_load_dwordx4 v[158:161], v[50:51], off offset:1024
	global_load_dwordx4 v[162:165], v[50:51], off offset:2064
	global_load_dwordx4 v[166:169], v[50:51], off offset:2048
	global_load_dwordx4 v[170:173], v[50:51], off offset:3088
	global_load_dwordx4 v[174:177], v[50:51], off offset:3072
	s_mov_b64 s[70:71], 0x1000
	v_lshl_add_u64 v[116:117], v[50:51], 0, s[70:71]
	global_load_dwordx4 v[178:181], v[116:117], off offset:16
	global_load_dwordx4 v[182:185], v[116:117], off
	global_load_dwordx4 v[186:189], v[116:117], off offset:1040
	global_load_dwordx4 v[190:193], v[116:117], off offset:1024
	global_load_dwordx4 v[202:205], v[116:117], off offset:2064
	global_load_dwordx4 v[206:209], v[116:117], off offset:2048
	global_load_dwordx4 v[210:213], v[116:117], off offset:3088
	global_load_dwordx4 v[214:217], v[116:117], off offset:3072
	v_lshlrev_b32_e32 v90, 16, v48
	v_and_b32_e32 v132, 0xffff0000, v48
	v_lshlrev_b32_e32 v134, 16, v49
	v_and_b32_e32 v136, 0xffff0000, v49
	v_lshlrev_b32_e32 v82, 16, v44
	v_and_b32_e32 v80, 0xffff0000, v44
	v_lshlrev_b32_e32 v78, 16, v45
	v_and_b32_e32 v76, 0xffff0000, v45
	v_lshlrev_b32_e32 v48, 16, v46
	v_and_b32_e32 v46, 0xffff0000, v46
	v_lshlrev_b32_e32 v44, 16, v47
	v_and_b32_e32 v74, 0xffff0000, v47
	s_mov_b32 s72, 0xbfb8aa3b
	s_mov_b32 s9, 0x7f800000
	s_mov_b32 s8, 0x3d800000
	s_mov_b64 s[70:71], 0x2000
	v_lshl_add_u64 v[126:127], v[50:51], 0, s[70:71]
	s_mov_b64 s[70:71], 0x3000
	v_lshl_add_u64 v[128:129], v[50:51], 0, s[70:71]
	s_waitcnt vmcnt(0)
	v_pk_fma_f32 v[118:119], v[90:91], v[146:147], v[138:139] op_sel_hi:[0,1,1]
	v_pk_fma_f32 v[120:121], v[90:91], v[148:149], v[140:141] op_sel_hi:[0,1,1]
	v_pk_fma_f32 v[122:123], v[90:91], v[150:151], v[142:143] op_sel_hi:[0,1,1]
	v_pk_fma_f32 v[124:125], v[90:91], v[152:153], v[144:145] op_sel_hi:[0,1,1]
	v_pk_fma_f32 v[118:119], v[132:133], v[154:155], v[118:119] op_sel_hi:[0,1,1]
	v_pk_fma_f32 v[120:121], v[132:133], v[156:157], v[120:121] op_sel_hi:[0,1,1]
	v_pk_fma_f32 v[122:123], v[132:133], v[158:159], v[122:123] op_sel_hi:[0,1,1]
	v_pk_fma_f32 v[124:125], v[132:133], v[160:161], v[124:125] op_sel_hi:[0,1,1]
	v_pk_fma_f32 v[118:119], v[134:135], v[162:163], v[118:119] op_sel_hi:[0,1,1]
	v_pk_fma_f32 v[120:121], v[134:135], v[164:165], v[120:121] op_sel_hi:[0,1,1]
	v_pk_fma_f32 v[122:123], v[134:135], v[166:167], v[122:123] op_sel_hi:[0,1,1]
	v_pk_fma_f32 v[124:125], v[134:135], v[168:169], v[124:125] op_sel_hi:[0,1,1]
	v_pk_fma_f32 v[118:119], v[136:137], v[170:171], v[118:119] op_sel_hi:[0,1,1]
	v_pk_fma_f32 v[120:121], v[136:137], v[172:173], v[120:121] op_sel_hi:[0,1,1]
	v_pk_fma_f32 v[122:123], v[136:137], v[174:175], v[122:123] op_sel_hi:[0,1,1]
	v_pk_fma_f32 v[124:125], v[136:137], v[176:177], v[124:125] op_sel_hi:[0,1,1]
	v_pk_fma_f32 v[118:119], v[92:93], v[178:179], v[118:119] op_sel_hi:[0,1,1]
	v_pk_fma_f32 v[120:121], v[92:93], v[180:181], v[120:121] op_sel_hi:[0,1,1]
	v_pk_fma_f32 v[122:123], v[92:93], v[182:183], v[122:123] op_sel_hi:[0,1,1]
	v_pk_fma_f32 v[124:125], v[92:93], v[184:185], v[124:125] op_sel_hi:[0,1,1]
	v_pk_fma_f32 v[118:119], v[88:89], v[186:187], v[118:119] op_sel_hi:[0,1,1]
	v_pk_fma_f32 v[120:121], v[88:89], v[188:189], v[120:121] op_sel_hi:[0,1,1]
	v_pk_fma_f32 v[122:123], v[88:89], v[190:191], v[122:123] op_sel_hi:[0,1,1]
	v_pk_fma_f32 v[124:125], v[88:89], v[192:193], v[124:125] op_sel_hi:[0,1,1]
	v_pk_fma_f32 v[118:119], v[86:87], v[202:203], v[118:119] op_sel_hi:[0,1,1]
	v_pk_fma_f32 v[120:121], v[86:87], v[204:205], v[120:121] op_sel_hi:[0,1,1]
	v_pk_fma_f32 v[122:123], v[86:87], v[206:207], v[122:123] op_sel_hi:[0,1,1]
	v_pk_fma_f32 v[124:125], v[86:87], v[208:209], v[124:125] op_sel_hi:[0,1,1]
	v_pk_fma_f32 v[118:119], v[84:85], v[210:211], v[118:119] op_sel_hi:[0,1,1]
	v_pk_fma_f32 v[120:121], v[84:85], v[212:213], v[120:121] op_sel_hi:[0,1,1]
	v_pk_fma_f32 v[122:123], v[84:85], v[214:215], v[122:123] op_sel_hi:[0,1,1]
	v_pk_fma_f32 v[124:125], v[84:85], v[216:217], v[124:125] op_sel_hi:[0,1,1]
	global_load_dwordx4 v[146:149], v[126:127], off offset:16
	global_load_dwordx4 v[150:153], v[126:127], off
	global_load_dwordx4 v[154:157], v[126:127], off offset:1040
	global_load_dwordx4 v[158:161], v[126:127], off offset:1024
	global_load_dwordx4 v[162:165], v[126:127], off offset:2064
	global_load_dwordx4 v[166:169], v[126:127], off offset:2048
	global_load_dwordx4 v[170:173], v[126:127], off offset:3088
	global_load_dwordx4 v[174:177], v[126:127], off offset:3072
	global_load_dwordx4 v[178:181], v[128:129], off offset:16
	global_load_dwordx4 v[182:185], v[128:129], off
	global_load_dwordx4 v[186:189], v[128:129], off offset:1040
	global_load_dwordx4 v[190:193], v[128:129], off offset:1024
	global_load_dwordx4 v[202:205], v[128:129], off offset:2064
	global_load_dwordx4 v[206:209], v[128:129], off offset:2048
	global_load_dwordx4 v[210:213], v[128:129], off offset:3088
	global_load_dwordx4 v[214:217], v[128:129], off offset:3072
	s_waitcnt vmcnt(0)
; __device__ __forceinline__ float logsigmoid_(float z) { return fminf(z, 0.f) - __logf(1.f + __expf(-fabsf(z))); }
; template <int TYPE>
; __device__ __forceinline__ void lg_compute(const KArgs& a, unsigned char* wsb, int l, int h, int dir, const LgRaw& raw, LAS unsigned char* lds, int tid) {
;     ...
;         for (int r = 0; r < 16; ++r) { z0 += ua[r] * *(const f32x4*)(up + r * 256); z1 += ua[r] * *(const f32x4*)(up + r * 256 + 4); }
;         f32x4 g0, g1;
; #pragma unroll
;         for (int e = 0; e < 4; ++e) { g0[e] = logsigmoid_(z0[e]) * (1.f / 16.f); g1[e] = logsigmoid_(z1[e]) * (1.f / 16.f); }
	v_pk_fma_f32 v[118:119], v[82:83], v[146:147], v[118:119] op_sel_hi:[0,1,1]
	v_pk_fma_f32 v[120:121], v[82:83], v[148:149], v[120:121] op_sel_hi:[0,1,1]
	v_pk_fma_f32 v[122:123], v[82:83], v[150:151], v[122:123] op_sel_hi:[0,1,1]
	v_pk_fma_f32 v[124:125], v[82:83], v[152:153], v[124:125] op_sel_hi:[0,1,1]
	v_pk_fma_f32 v[118:119], v[80:81], v[154:155], v[118:119] op_sel_hi:[0,1,1]
	v_pk_fma_f32 v[120:121], v[80:81], v[156:157], v[120:121] op_sel_hi:[0,1,1]
	v_pk_fma_f32 v[122:123], v[80:81], v[158:159], v[122:123] op_sel_hi:[0,1,1]
	v_pk_fma_f32 v[124:125], v[80:81], v[160:161], v[124:125] op_sel_hi:[0,1,1]
	v_pk_fma_f32 v[118:119], v[78:79], v[162:163], v[118:119] op_sel_hi:[0,1,1]
	v_pk_fma_f32 v[120:121], v[78:79], v[164:165], v[120:121] op_sel_hi:[0,1,1]
	v_pk_fma_f32 v[122:123], v[78:79], v[166:167], v[122:123] op_sel_hi:[0,1,1]
	v_pk_fma_f32 v[124:125], v[78:79], v[168:169], v[124:125] op_sel_hi:[0,1,1]
	v_pk_fma_f32 v[118:119], v[76:77], v[170:171], v[118:119] op_sel_hi:[0,1,1]
	v_pk_fma_f32 v[120:121], v[76:77], v[172:173], v[120:121] op_sel_hi:[0,1,1]
	v_pk_fma_f32 v[122:123], v[76:77], v[174:175], v[122:123] op_sel_hi:[0,1,1]
	v_pk_fma_f32 v[124:125], v[76:77], v[176:177], v[124:125] op_sel_hi:[0,1,1]
	v_pk_fma_f32 v[118:119], v[48:49], v[178:179], v[118:119] op_sel_hi:[0,1,1]
	v_pk_fma_f32 v[120:121], v[48:49], v[180:181], v[120:121] op_sel_hi:[0,1,1]
	v_pk_fma_f32 v[122:123], v[48:49], v[182:183], v[122:123] op_sel_hi:[0,1,1]
	v_pk_fma_f32 v[124:125], v[48:49], v[184:185], v[124:125] op_sel_hi:[0,1,1]
	v_pk_fma_f32 v[118:119], v[46:47], v[186:187], v[118:119] op_sel_hi:[0,1,1]
	v_pk_fma_f32 v[120:121], v[46:47], v[188:189], v[120:121] op_sel_hi:[0,1,1]
	v_pk_fma_f32 v[122:123], v[46:47], v[190:191], v[122:123] op_sel_hi:[0,1,1]
	v_pk_fma_f32 v[124:125], v[46:47], v[192:193], v[124:125] op_sel_hi:[0,1,1]
	v_pk_fma_f32 v[118:119], v[44:45], v[202:203], v[118:119] op_sel_hi:[0,1,1]
	v_pk_fma_f32 v[120:121], v[44:45], v[204:205], v[120:121] op_sel_hi:[0,1,1]
	v_pk_fma_f32 v[122:123], v[44:45], v[206:207], v[122:123] op_sel_hi:[0,1,1]
	v_pk_fma_f32 v[124:125], v[44:45], v[208:209], v[124:125] op_sel_hi:[0,1,1]
	v_pk_fma_f32 v[78:79], v[74:75], v[214:215], v[122:123] op_sel_hi:[0,1,1]
	v_pk_fma_f32 v[46:47], v[74:75], v[216:217], v[124:125] op_sel_hi:[0,1,1]
	v_pk_fma_f32 v[44:45], v[74:75], v[212:213], v[120:121] op_sel_hi:[0,1,1]
	v_pk_fma_f32 v[74:75], v[74:75], v[210:211], v[118:119] op_sel_hi:[0,1,1]
	v_mul_f32_e64 v48, |v78|, s72
	v_exp_f32_e32 v48, v48
	v_min_f32_e32 v50, 0, v78
	v_min_f32_e32 v80, 0, v44
	v_mul_f32_e64 v44, |v44|, s72
	v_add_f32_e32 v48, 1.0, v48
	v_cmp_gt_f32_e32 vcc, s33, v48
	v_exp_f32_e32 v44, v44
	s_nop 0
	v_cndmask_b32_e64 v49, 0, 32, vcc
	v_ldexp_f32 v48, v48, v49
	v_log_f32_e32 v48, v48
	v_add_f32_e32 v44, 1.0, v44
	v_mul_f32_e32 v49, 0x3f317217, v48
	v_fma_f32 v49, v48, s92, -v49
	v_fmac_f32_e32 v49, 0x3377d1cf, v48
	v_fmac_f32_e32 v49, 0x3f317217, v48
	v_cmp_lt_f32_e64 s[70:71], |v48|, s9
	s_nop 1
	v_cndmask_b32_e64 v48, v48, v49, s[70:71]
	v_cndmask_b32_e32 v49, 0, v238, vcc
	v_sub_f32_e32 v76, v48, v49
	v_mul_f32_e64 v49, |v74|, s72
	v_exp_f32_e32 v49, v49
	v_min_f32_e32 v48, 0, v74
	v_add_f32_e32 v49, 1.0, v49
	v_cmp_gt_f32_e32 vcc, s33, v49
	s_nop 1
	v_cndmask_b32_e64 v51, 0, 32, vcc
	v_ldexp_f32 v49, v49, v51
	v_log_f32_e32 v49, v49
	s_nop 0
	v_mul_f32_e32 v51, 0x3f317217, v49
	v_fma_f32 v51, v49, s92, -v51
	v_fmac_f32_e32 v51, 0x3377d1cf, v49
	v_fmac_f32_e32 v51, 0x3f317217, v49
	v_cmp_lt_f32_e64 s[70:71], |v49|, s9
	s_nop 1
	v_cndmask_b32_e64 v49, v49, v51, s[70:71]
	v_cndmask_b32_e32 v51, 0, v238, vcc
	v_sub_f32_e32 v74, v49, v51
	v_mul_f32_e64 v49, |v79|, s72
	v_exp_f32_e32 v49, v49
	v_min_f32_e32 v51, 0, v79
	v_add_f32_e32 v49, 1.0, v49
	v_cmp_gt_f32_e32 vcc, s33, v49
	s_nop 1
	v_cndmask_b32_e64 v77, 0, 32, vcc
	v_ldexp_f32 v49, v49, v77
	v_log_f32_e32 v49, v49
	s_nop 0
	v_mul_f32_e32 v77, 0x3f317217, v49
	v_fma_f32 v77, v49, s92, -v77
	v_fmac_f32_e32 v77, 0x3377d1cf, v49
	v_fmac_f32_e32 v77, 0x3f317217, v49
	v_cmp_lt_f32_e64 s[70:71], |v49|, s9
	s_nop 1
	v_cndmask_b32_e64 v49, v49, v77, s[70:71]
	v_cndmask_b32_e32 v77, 0, v238, vcc
	v_sub_f32_e32 v77, v49, v77
	v_min_f32_e32 v49, 0, v75
	v_mul_f32_e64 v75, |v75|, s72
	v_exp_f32_e32 v75, v75
	v_pk_add_f32 v[50:51], v[50:51], v[76:77] neg_lo:[0,1] neg_hi:[0,1]
	v_add_f32_e32 v75, 1.0, v75
	v_cmp_gt_f32_e32 vcc, s33, v75
; #define LAS __attribute__((address_space(3)))
; __device__ __forceinline__ float logsigmoid_(float z) { return fminf(z, 0.f) - __logf(1.f + __expf(-fabsf(z))); }
; template <int TYPE>
; __device__ __forceinline__ void lg_compute(const KArgs& a, unsigned char* wsb, int l, int h, int dir, const LgRaw& raw, LAS unsigned char* lds, int tid) {
;     ...
;         for (int e = 0; e < 4; ++e) { g0[e] = logsigmoid_(z0[e]) * (1.f / 16.f); g1[e] = logsigmoid_(z1[e]) * (1.f / 16.f); }
;         *(LAS f32x4*)(G + i * C::LDG + d8 * 8) = g0; *(LAS f32x4*)(G + i * C::LDG + d8 * 8 + 4) = g1;
;         *(LAS bf16x8*)(Kb + i * C::LDK_ + d8 * 8) = raw.k;
;     }
; }
; template <int TYPE>
; __device__ __forceinline__ void cumsum_g(int dir, LAS unsigned char* lds, int tid) {
;     using C = Cfg<TYPE>; constexpr int NSEG = 512 / C::DK, SEGL = 64 / NSEG;
;     LAS float* G = (LAS float*)(lds + SC_G); LAS float* SG = (LAS float*)(lds + SC_SEG);
;     const int d = tid % C::DK, seg = tid / C::DK;
;     __syncthreads();
;     float run = 0.f;
; #pragma unroll
;     for (int ii = 0; ii < SEGL; ++ii) { const int i = seg * SEGL + (dir ? SEGL - 1 - ii : ii); run += G[i * C::LDG + d]; G[i * C::LDG + d] = run; }
	v_pk_mul_f32 v[76:77], v[50:51], s[8:9] op_sel_hi:[1,0]
	s_nop 0
	v_cndmask_b32_e64 v78, 0, 32, vcc
	v_ldexp_f32 v75, v75, v78
	v_log_f32_e32 v75, v75
	s_nop 0
	v_mul_f32_e32 v78, 0x3f317217, v75
	v_fma_f32 v78, v75, s92, -v78
	v_fmac_f32_e32 v78, 0x3377d1cf, v75
	v_fmac_f32_e32 v78, 0x3f317217, v75
	v_cmp_lt_f32_e64 s[70:71], |v75|, s9
	s_nop 1
	v_cndmask_b32_e64 v75, v75, v78, s[70:71]
	v_cndmask_b32_e32 v78, 0, v238, vcc
	v_sub_f32_e32 v75, v75, v78
	v_min_f32_e32 v78, 0, v46
	v_mul_f32_e64 v46, |v46|, s72
	v_exp_f32_e32 v46, v46
	s_nop 0
	v_add_f32_e32 v46, 1.0, v46
	v_cmp_gt_f32_e32 vcc, s33, v46
	s_nop 1
	v_cndmask_b32_e64 v79, 0, 32, vcc
	v_ldexp_f32 v46, v46, v79
	v_log_f32_e32 v46, v46
	s_nop 0
	v_mul_f32_e32 v79, 0x3f317217, v46
	v_fma_f32 v79, v46, s92, -v79
	v_fmac_f32_e32 v79, 0x3377d1cf, v46
	v_fmac_f32_e32 v79, 0x3f317217, v46
	v_cmp_lt_f32_e64 s[70:71], |v46|, s9
	s_nop 1
	v_cndmask_b32_e64 v46, v46, v79, s[70:71]
	v_cndmask_b32_e32 v79, 0, v238, vcc
	v_cmp_gt_f32_e32 vcc, s33, v44
	v_sub_f32_e32 v46, v46, v79
	s_nop 0
	v_cndmask_b32_e64 v79, 0, 32, vcc
	v_ldexp_f32 v44, v44, v79
	v_log_f32_e32 v44, v44
	s_nop 0
	v_mul_f32_e32 v79, 0x3f317217, v44
	v_fma_f32 v79, v44, s92, -v79
	v_fmac_f32_e32 v79, 0x3377d1cf, v44
	v_fmac_f32_e32 v79, 0x3f317217, v44
	v_cmp_lt_f32_e64 s[70:71], |v44|, s9
	s_nop 1
	v_cndmask_b32_e64 v44, v44, v79, s[70:71]
	v_cndmask_b32_e32 v79, 0, v238, vcc
	v_sub_f32_e32 v44, v44, v79
	v_min_f32_e32 v79, 0, v47
	v_mul_f32_e64 v47, |v47|, s72
	v_exp_f32_e32 v47, v47
	s_nop 0
	v_add_f32_e32 v47, 1.0, v47
	v_cmp_gt_f32_e32 vcc, s33, v47
	s_nop 1
	v_cndmask_b32_e64 v81, 0, 32, vcc
	v_ldexp_f32 v47, v47, v81
	v_log_f32_e32 v47, v47
	s_nop 0
	v_mul_f32_e32 v81, 0x3f317217, v47
	v_fma_f32 v81, v47, s92, -v81
	v_fmac_f32_e32 v81, 0x3377d1cf, v47
	v_fmac_f32_e32 v81, 0x3f317217, v47
	v_cmp_lt_f32_e64 s[70:71], |v47|, s9
	s_nop 1
	v_cndmask_b32_e64 v47, v47, v81, s[70:71]
	v_cndmask_b32_e32 v81, 0, v238, vcc
	v_sub_f32_e32 v47, v47, v81
	v_min_f32_e32 v81, 0, v45
	v_mul_f32_e64 v45, |v45|, s72
	v_exp_f32_e32 v45, v45
	v_pk_add_f32 v[46:47], v[78:79], v[46:47] neg_lo:[0,1] neg_hi:[0,1]
	s_movk_i32 s72, 0x110
	v_pk_mul_f32 v[78:79], v[46:47], s[8:9] op_sel_hi:[1,0]
	v_add_f32_e32 v45, 1.0, v45
	v_cmp_gt_f32_e32 vcc, s33, v45
	s_nop 1
	v_cndmask_b32_e64 v46, 0, 32, vcc
	v_ldexp_f32 v45, v45, v46
	v_log_f32_e32 v45, v45
	s_nop 0
	v_mul_f32_e32 v46, 0x3f317217, v45
	v_fma_f32 v46, v45, s92, -v46
	v_fmac_f32_e32 v46, 0x3377d1cf, v45
	v_fmac_f32_e32 v46, 0x3f317217, v45
	v_cmp_lt_f32_e64 s[70:71], |v45|, s9
	s_nop 1
	v_cndmask_b32_e64 v45, v45, v46, s[70:71]
	v_cndmask_b32_e32 v46, 0, v238, vcc
	v_sub_f32_e32 v45, v45, v46
	v_pk_add_f32 v[46:47], v[48:49], v[74:75] neg_lo:[0,1] neg_hi:[0,1]
	v_pk_add_f32 v[48:49], v[80:81], v[44:45] neg_lo:[0,1] neg_hi:[0,1]
	v_pk_mul_f32 v[44:45], v[46:47], s[8:9] op_sel_hi:[1,0]
	v_pk_mul_f32 v[46:47], v[48:49], s[8:9] op_sel_hi:[1,0]
	ds_write_b128 v83, v[76:79]
	ds_write_b128 v83, v[44:47] offset:16
	ds_write_b128 v85, v[20:23] offset:33792
	v_or_b32_e32 v44, s76, v87
	v_mad_u64_u32 v[44:45], s[70:71], v44, s72, v[66:67]
	s_waitcnt lgkmcnt(0)
	s_barrier
	ds_read_b32 v158, v44
	v_or_b32_e32 v142, s93, v87
	v_mad_u64_u32 v[142:143], s[70:71], v142, s72, v[66:67]
	ds_read_b32 v159, v142
	s_movk_i32 s93, 0x110
	v_or_b32_e32 v144, s79, v87
	v_mad_u64_u32 v[144:145], s[70:71], v144, s72, v[66:67]
	ds_read_b32 v160, v144
	v_or_b32_e32 v146, s78, v87
	v_mad_u64_u32 v[146:147], s[70:71], v146, s72, v[66:67]
	ds_read_b32 v161, v146
	v_or_b32_e32 v148, s75, v87
	v_mad_u64_u32 v[148:149], s[70:71], v148, s72, v[66:67]
	ds_read_b32 v162, v148
	v_or_b32_e32 v150, s74, v87
	v_mad_u64_u32 v[150:151], s[70:71], v150, s72, v[66:67]
	ds_read_b32 v163, v150
	v_or_b32_e32 v152, s4, v87
	v_mad_u64_u32 v[152:153], s[70:71], v152, s72, v[66:67]
	ds_read_b32 v164, v152
	v_or_b32_e32 v154, s80, v87
	v_mad_u64_u32 v[154:155], s[70:71], v154, s72, v[66:67]
	ds_read_b32 v165, v154
	s_waitcnt lgkmcnt(0)
	v_add_f32_e32 v46, 0, v158
	ds_write_b32 v44, v46
	v_add_f32_e32 v46, v46, v159
	ds_write_b32 v142, v46
	v_add_f32_e32 v46, v46, v160
	ds_write_b32 v144, v46
	v_add_f32_e32 v46, v46, v161
	ds_write_b32 v146, v46
	v_add_f32_e32 v46, v46, v162
	ds_write_b32 v148, v46
	v_add_f32_e32 v46, v46, v163
	ds_write_b32 v150, v46
	v_add_f32_e32 v46, v46, v164
	ds_write_b32 v152, v46
	v_add_f32_e32 v45, v46, v165
	ds_write_b32 v154, v45


; template <int TYPE>
; __device__ __forceinline__ void cumsum_g(int dir, LAS unsigned char* lds, int tid) {
;     ...
;     SG[seg * 128 + d] = run;
;     __syncthreads();
;     float off = 0.f;
; #pragma unroll
;     for (int s = 0; s < NSEG; ++s) { const bool before = dir ? (s > seg) : (s < seg); if (before) off += SG[s * 128 + d]; }
	ds_write_b32 v93, v45
	v_mov_b32_e32 v44, 0
	s_waitcnt lgkmcnt(0)
	s_barrier
	s_and_saveexec_b64 s[70:71], s[86:87]
	s_cbranch_execz .LBB0_517
	ds_read_b32 v44, v89
	s_waitcnt lgkmcnt(0)
	v_add_f32_e32 v44, 0, v44
